# as previous plus: vmcnt(0) drains removed from the simple G1 epilogue sections (3,6,7) whose only loads were the hoisted rs
# speedup vs baseline: 1.0212x; 1.0086x over previous
.Lsec78_a:
	s_lshl_b32 s0, s48, 8
	v_add_u32_e32 v134, s0, v241
	v_ashrrev_i32_e32 v135, 31, v134
	v_lshl_add_u64 v[146:147], v[134:135], 2, s[70:71]
	v_mov_b32_e32 v148, v164
	v_mov_b32_e32 v144, v165
	v_mov_b32_e32 v140, v166
	v_mov_b32_e32 v2, v167
	v_or_b32_e32 v132, s74, v178
	v_ashrrev_i32_e32 v133, 31, v132
	v_lshlrev_b64 v[132:133], 1, v[132:133]
	s_mov_b32 s0, 0x9ce6000
	s_cmp_eq_u32 s2, 8
	s_cselect_b32 s0, 0xbd25800, s0
	v_or_b32_e32 v142, 16, v134
	v_ashrrev_i32_e32 v143, 31, v142
	v_lshlrev_b64 v[142:143], 11, v[142:143]
	v_lshl_add_u64 v[142:143], s[94:95], 0, v[142:143]
	v_or_b32_e32 v138, 32, v134
	v_ashrrev_i32_e32 v139, 31, v138
	v_lshlrev_b64 v[138:139], 11, v[138:139]
	v_lshl_add_u64 v[138:139], s[94:95], 0, v[138:139]
	v_or_b32_e32 v136, 48, v134
	v_ashrrev_i32_e32 v137, 31, v136
	v_lshlrev_b64 v[136:137], 11, v[136:137]
	v_lshl_add_u64 v[136:137], s[94:95], 0, v[136:137]
	s_cmp_eq_u32 s48, 64
	v_pk_mul_f32 v[146:147], v[130:131], v[148:149] op_sel_hi:[1,0]
	s_nop 0
	v_mul_f32_e32 v146, 0xbfb8aa3b, v146
	v_exp_f32_e32 v146, v146
	v_pk_mul_f32 v[150:151], v[128:129], v[148:149] op_sel_hi:[1,0]
	v_add_f32_e32 v146, 1.0, v146
	v_rcp_f32_e32 v152, v146
	v_mul_f32_e32 v146, 0xbfb8aa3b, v147
	v_exp_f32_e32 v146, v146
	v_mul_f32_e32 v141, 0xbfb8aa3b, v150
	v_mul_f32_e32 v145, 0xbfb8aa3b, v151
	v_exp_f32_e32 v141, v141
	v_add_f32_e32 v146, 1.0, v146
	v_rcp_f32_e32 v153, v146
	v_pk_mul_f32 v[146:147], v[126:127], v[148:149] op_sel_hi:[1,0]
	v_pk_mul_f32 v[148:149], v[124:125], v[148:149] op_sel_hi:[1,0]
	v_mul_f32_e32 v146, 0xbfb8aa3b, v146
	v_exp_f32_e32 v146, v146
	v_mul_f32_e32 v148, 0xbfb8aa3b, v148
	v_mul_f32_e32 v149, 0xbfb8aa3b, v149
	v_exp_f32_e32 v145, v145
	v_add_f32_e32 v146, 1.0, v146
	v_rcp_f32_e32 v154, v146
	v_mul_f32_e32 v146, 0xbfb8aa3b, v147
	v_exp_f32_e32 v148, v148
	v_exp_f32_e32 v149, v149
	v_exp_f32_e32 v146, v146
	v_add_f32_e32 v141, 1.0, v141
	v_add_f32_e32 v145, 1.0, v145
	v_add_f32_e32 v148, 1.0, v148
	v_add_f32_e32 v149, 1.0, v149
	v_add_f32_e32 v146, 1.0, v146
	v_rcp_f32_e32 v141, v141
	v_rcp_f32_e32 v145, v145
	v_rcp_f32_e32 v148, v148
	v_rcp_f32_e32 v149, v149
	v_rcp_f32_e32 v155, v146
	v_lshlrev_b64 v[146:147], 11, v[134:135]
	v_lshl_add_u64 v[146:147], s[94:95], 0, v[146:147]
	v_lshl_add_u64 v[150:151], v[146:147], 0, v[132:133]
	v_add_co_u32_e32 v150, vcc, s0, v150
	v_cvt_pk_bf16_f32 v146, v141, v145
	v_cvt_pk_bf16_f32 v147, v152, v153
	v_cvt_pk_bf16_f32 v148, v148, v149
	v_cvt_pk_bf16_f32 v149, v154, v155
	v_addc_co_u32_e32 v151, vcc, 0, v151, vcc
	global_store_dwordx4 v[150:151], v[146:149], off offset:512
	s_nop 1
	v_pk_mul_f32 v[146:147], v[122:123], v[144:145] op_sel_hi:[1,0]
	v_pk_mul_f32 v[148:149], v[120:121], v[144:145] op_sel_hi:[1,0]
	v_mul_f32_e32 v145, 0xbfb8aa3b, v146
	v_exp_f32_e32 v145, v145
	v_mul_f32_e32 v135, 0xbfb8aa3b, v148
	v_mul_f32_e32 v141, 0xbfb8aa3b, v149
	v_exp_f32_e32 v135, v135
	v_add_f32_e32 v145, 1.0, v145
	v_rcp_f32_e32 v148, v145
	v_mul_f32_e32 v145, 0xbfb8aa3b, v147
	v_exp_f32_e32 v145, v145
	v_exp_f32_e32 v141, v141
	v_add_f32_e32 v135, 1.0, v135
	v_rcp_f32_e32 v135, v135
	v_add_f32_e32 v145, 1.0, v145
	v_pk_mul_f32 v[146:147], v[118:119], v[144:145] op_sel_hi:[1,0]
	v_rcp_f32_e32 v149, v145
	v_mul_f32_e32 v146, 0xbfb8aa3b, v146
	v_exp_f32_e32 v146, v146
	v_pk_mul_f32 v[144:145], v[116:117], v[144:145] op_sel_hi:[1,0]
	v_add_f32_e32 v141, 1.0, v141
	v_mul_f32_e32 v144, 0xbfb8aa3b, v144
	v_add_f32_e32 v146, 1.0, v146
	v_mul_f32_e32 v145, 0xbfb8aa3b, v145
	v_rcp_f32_e32 v150, v146
	v_mul_f32_e32 v146, 0xbfb8aa3b, v147
	v_exp_f32_e32 v144, v144
	v_exp_f32_e32 v145, v145
	v_exp_f32_e32 v146, v146
	v_rcp_f32_e32 v141, v141
	v_add_f32_e32 v144, 1.0, v144
	v_add_f32_e32 v145, 1.0, v145
	v_add_f32_e32 v146, 1.0, v146
	v_rcp_f32_e32 v144, v144
	v_rcp_f32_e32 v145, v145
	v_rcp_f32_e32 v151, v146
	v_lshl_add_u64 v[146:147], v[142:143], 0, v[132:133]
	v_add_co_u32_e32 v146, vcc, s0, v146
	v_cvt_pk_bf16_f32 v142, v135, v141
	v_cvt_pk_bf16_f32 v143, v148, v149
	v_cvt_pk_bf16_f32 v144, v144, v145
	v_cvt_pk_bf16_f32 v145, v150, v151
	v_addc_co_u32_e32 v147, vcc, 0, v147, vcc
	global_store_dwordx4 v[146:147], v[142:145], off offset:512
	s_nop 1
	v_pk_mul_f32 v[144:145], v[112:113], v[140:141] op_sel_hi:[1,0]
	v_pk_mul_f32 v[142:143], v[114:115], v[140:141] op_sel_hi:[1,0]
	v_mul_f32_e32 v141, 0xbfb8aa3b, v145
	v_exp_f32_e32 v141, v141
	v_mul_f32_e32 v135, 0xbfb8aa3b, v144
	v_exp_f32_e32 v135, v135
	v_add_f32_e32 v141, 1.0, v141
	v_rcp_f32_e32 v144, v141
	v_mul_f32_e32 v141, 0xbfb8aa3b, v142
	v_exp_f32_e32 v141, v141
	v_add_f32_e32 v135, 1.0, v135
	v_rcp_f32_e32 v135, v135
	v_add_f32_e32 v141, 1.0, v141
	v_rcp_f32_e32 v145, v141
	v_mul_f32_e32 v141, 0xbfb8aa3b, v143
	v_exp_f32_e32 v141, v141
	s_nop 0
	v_add_f32_e32 v141, 1.0, v141
	v_pk_mul_f32 v[142:143], v[110:111], v[140:141] op_sel_hi:[1,0]
	v_rcp_f32_e32 v146, v141
	v_mul_f32_e32 v142, 0xbfb8aa3b, v142
	v_exp_f32_e32 v142, v142
	v_pk_mul_f32 v[140:141], v[108:109], v[140:141] op_sel_hi:[1,0]
	v_add_f32_e32 v142, 1.0, v142
	v_mul_f32_e32 v140, 0xbfb8aa3b, v140
	v_mul_f32_e32 v141, 0xbfb8aa3b, v141
	v_rcp_f32_e32 v147, v142
	v_mul_f32_e32 v142, 0xbfb8aa3b, v143
	v_exp_f32_e32 v140, v140
	v_exp_f32_e32 v141, v141
	v_exp_f32_e32 v142, v142
	v_add_f32_e32 v140, 1.0, v140
	v_add_f32_e32 v141, 1.0, v141
	v_add_f32_e32 v142, 1.0, v142
	v_rcp_f32_e32 v140, v140
	v_rcp_f32_e32 v141, v141
	v_rcp_f32_e32 v148, v142
	v_lshl_add_u64 v[142:143], v[138:139], 0, v[132:133]
	v_add_co_u32_e32 v142, vcc, s0, v142
	v_cvt_pk_bf16_f32 v138, v135, v144
	v_cvt_pk_bf16_f32 v139, v145, v146
	v_cvt_pk_bf16_f32 v140, v140, v141
	v_cvt_pk_bf16_f32 v141, v147, v148
	v_addc_co_u32_e32 v143, vcc, 0, v143, vcc
	global_store_dwordx4 v[142:143], v[138:141], off offset:512
	s_nop 1
	v_pk_mul_f32 v[138:139], v[106:107], v[2:3] op_sel_hi:[1,0]
	v_pk_mul_f32 v[140:141], v[104:105], v[2:3] op_sel_hi:[1,0]
	v_mul_f32_e32 v138, 0xbfb8aa3b, v138
	v_exp_f32_e32 v138, v138
	v_mul_f32_e32 v135, 0xbfb8aa3b, v140
	v_mul_f32_e32 v140, 0xbfb8aa3b, v141
	v_exp_f32_e32 v140, v140
	v_add_f32_e32 v138, 1.0, v138
	v_rcp_f32_e32 v143, v138
	v_mul_f32_e32 v138, 0xbfb8aa3b, v139
	v_exp_f32_e32 v138, v138
	v_add_f32_e32 v140, 1.0, v140
	v_rcp_f32_e32 v142, v140
	v_pk_mul_f32 v[140:141], v[100:101], v[2:3] op_sel_hi:[1,0]
	v_add_f32_e32 v138, 1.0, v138
	v_rcp_f32_e32 v144, v138
	v_pk_mul_f32 v[138:139], v[102:103], v[2:3] op_sel_hi:[1,0]
	v_mul_f32_e32 v2, 0xbfb8aa3b, v140
	v_mul_f32_e32 v138, 0xbfb8aa3b, v138
	v_exp_f32_e32 v138, v138
	v_mul_f32_e32 v140, 0xbfb8aa3b, v141
	v_exp_f32_e32 v135, v135
	v_exp_f32_e32 v2, v2
	v_add_f32_e32 v138, 1.0, v138
	v_rcp_f32_e32 v146, v138
	v_mul_f32_e32 v138, 0xbfb8aa3b, v139
	v_exp_f32_e32 v140, v140
	v_exp_f32_e32 v138, v138
	v_add_f32_e32 v135, 1.0, v135
	v_add_f32_e32 v2, 1.0, v2
	v_add_f32_e32 v140, 1.0, v140
	v_add_f32_e32 v138, 1.0, v138
	v_rcp_f32_e32 v135, v135
	v_rcp_f32_e32 v2, v2
	v_rcp_f32_e32 v145, v140
	v_rcp_f32_e32 v139, v138
	v_lshl_add_u64 v[140:141], v[136:137], 0, v[132:133]
	v_add_co_u32_e32 v140, vcc, s0, v140
	v_cvt_pk_bf16_f32 v136, v135, v142
	v_cvt_pk_bf16_f32 v137, v143, v144
	v_cvt_pk_bf16_f32 v138, v2, v145
	v_cvt_pk_bf16_f32 v139, v146, v139
	v_addc_co_u32_e32 v141, vcc, 0, v141, vcc
	global_store_dwordx4 v[140:141], v[136:139], off offset:512
	s_cbranch_scc1 .LBB0_70
	v_add_u32_e32 v144, 0x80, v134
	v_ashrrev_i32_e32 v145, 31, v144
	v_lshl_add_u64 v[146:147], v[144:145], 2, s[70:71]
	v_mov_b32_e32 v148, v246
	v_mov_b32_e32 v142, v247
	v_mov_b32_e32 v138, v248
	v_mov_b32_e32 v2, v249
	v_lshlrev_b64 v[144:145], 11, v[144:145]
	v_lshl_add_u64 v[144:145], s[94:95], 0, v[144:145]
	v_add_u32_e32 v140, 0x90, v134
	v_ashrrev_i32_e32 v141, 31, v140
	v_lshlrev_b64 v[140:141], 11, v[140:141]
	v_lshl_add_u64 v[140:141], s[94:95], 0, v[140:141]
	v_add_u32_e32 v136, 0xa0, v134
	v_ashrrev_i32_e32 v137, 31, v136
	v_lshlrev_b64 v[136:137], 11, v[136:137]
	v_lshl_add_u64 v[136:137], s[94:95], 0, v[136:137]
	v_add_u32_e32 v134, 0xb0, v134
	v_ashrrev_i32_e32 v135, 31, v134
	v_lshlrev_b64 v[134:135], 11, v[134:135]
	v_lshl_add_u64 v[134:135], s[94:95], 0, v[134:135]
	v_pk_mul_f32 v[146:147], v[98:99], v[148:149] op_sel_hi:[1,0]
	s_nop 0
	v_mul_f32_e32 v146, 0xbfb8aa3b, v146
	v_exp_f32_e32 v146, v146
	v_pk_mul_f32 v[150:151], v[96:97], v[148:149] op_sel_hi:[1,0]
	v_add_f32_e32 v146, 1.0, v146
	v_mul_f32_e32 v139, 0xbfb8aa3b, v150
	v_rcp_f32_e32 v150, v146
	v_mul_f32_e32 v146, 0xbfb8aa3b, v147
	v_exp_f32_e32 v146, v146
	v_mul_f32_e32 v143, 0xbfb8aa3b, v151
	v_exp_f32_e32 v139, v139
	v_exp_f32_e32 v143, v143
	v_add_f32_e32 v146, 1.0, v146
	v_rcp_f32_e32 v151, v146
	v_pk_mul_f32 v[146:147], v[94:95], v[148:149] op_sel_hi:[1,0]
	v_pk_mul_f32 v[148:149], v[92:93], v[148:149] op_sel_hi:[1,0]
	v_mul_f32_e32 v146, 0xbfb8aa3b, v146
	v_mul_f32_e32 v148, 0xbfb8aa3b, v148
	v_exp_f32_e32 v148, v148
	v_exp_f32_e32 v146, v146
	v_add_f32_e32 v139, 1.0, v139
	v_add_f32_e32 v143, 1.0, v143
	v_add_f32_e32 v148, 1.0, v148
	v_add_f32_e32 v146, 1.0, v146
	v_rcp_f32_e32 v152, v148
	v_mul_f32_e32 v148, 0xbfb8aa3b, v149
	v_rcp_f32_e32 v154, v146
	v_mul_f32_e32 v146, 0xbfb8aa3b, v147
	v_exp_f32_e32 v148, v148
	v_exp_f32_e32 v146, v146
	v_rcp_f32_e32 v139, v139
	v_rcp_f32_e32 v143, v143
	v_add_f32_e32 v148, 1.0, v148
	v_add_f32_e32 v146, 1.0, v146
	v_rcp_f32_e32 v153, v148
	v_rcp_f32_e32 v147, v146
	v_lshl_add_u64 v[148:149], v[144:145], 0, v[132:133]
	v_add_co_u32_e32 v148, vcc, s0, v148
	v_cvt_pk_bf16_f32 v144, v139, v143
	v_cvt_pk_bf16_f32 v145, v150, v151
	v_cvt_pk_bf16_f32 v146, v152, v153
	v_cvt_pk_bf16_f32 v147, v154, v147
	v_addc_co_u32_e32 v149, vcc, 0, v149, vcc
	global_store_dwordx4 v[148:149], v[144:147], off offset:512
	s_nop 1
	v_pk_mul_f32 v[146:147], v[88:89], v[142:143] op_sel_hi:[1,0]
	v_pk_mul_f32 v[144:145], v[90:91], v[142:143] op_sel_hi:[1,0]
	v_mul_f32_e32 v143, 0xbfb8aa3b, v147
	v_exp_f32_e32 v143, v143
	v_mul_f32_e32 v139, 0xbfb8aa3b, v146
	v_exp_f32_e32 v139, v139
	v_add_f32_e32 v143, 1.0, v143
	v_rcp_f32_e32 v146, v143
	v_mul_f32_e32 v143, 0xbfb8aa3b, v144
	v_exp_f32_e32 v143, v143
	v_add_f32_e32 v139, 1.0, v139
	v_rcp_f32_e32 v139, v139
	v_add_f32_e32 v143, 1.0, v143
	v_rcp_f32_e32 v147, v143
	v_mul_f32_e32 v143, 0xbfb8aa3b, v145
	v_exp_f32_e32 v143, v143
	s_nop 0
	v_add_f32_e32 v143, 1.0, v143
	v_pk_mul_f32 v[144:145], v[86:87], v[142:143] op_sel_hi:[1,0]
	v_rcp_f32_e32 v148, v143
	v_mul_f32_e32 v144, 0xbfb8aa3b, v144
	v_exp_f32_e32 v144, v144
	v_pk_mul_f32 v[142:143], v[84:85], v[142:143] op_sel_hi:[1,0]
	v_add_f32_e32 v144, 1.0, v144
	v_mul_f32_e32 v142, 0xbfb8aa3b, v142
	v_mul_f32_e32 v143, 0xbfb8aa3b, v143
	v_rcp_f32_e32 v149, v144
	v_mul_f32_e32 v144, 0xbfb8aa3b, v145
	v_exp_f32_e32 v142, v142
	v_exp_f32_e32 v143, v143
	v_exp_f32_e32 v144, v144
	v_add_f32_e32 v142, 1.0, v142
	v_add_f32_e32 v143, 1.0, v143
	v_add_f32_e32 v144, 1.0, v144
	v_rcp_f32_e32 v142, v142
	v_rcp_f32_e32 v143, v143
	v_rcp_f32_e32 v150, v144
	v_lshl_add_u64 v[144:145], v[140:141], 0, v[132:133]
	v_add_co_u32_e32 v144, vcc, s0, v144
	v_cvt_pk_bf16_f32 v140, v139, v146
	v_cvt_pk_bf16_f32 v141, v147, v148
	v_cvt_pk_bf16_f32 v142, v142, v143
	v_cvt_pk_bf16_f32 v143, v149, v150
	v_addc_co_u32_e32 v145, vcc, 0, v145, vcc
	global_store_dwordx4 v[144:145], v[140:143], off offset:512
	s_nop 1
	v_pk_mul_f32 v[142:143], v[80:81], v[138:139] op_sel_hi:[1,0]
	v_pk_mul_f32 v[140:141], v[82:83], v[138:139] op_sel_hi:[1,0]
	v_mul_f32_e32 v139, 0xbfb8aa3b, v142
	v_exp_f32_e32 v139, v139
	s_nop 0
	v_add_f32_e32 v139, 1.0, v139
	v_rcp_f32_e32 v142, v139
	v_mul_f32_e32 v139, 0xbfb8aa3b, v143
	v_exp_f32_e32 v139, v139
	s_nop 0
	v_add_f32_e32 v139, 1.0, v139
	v_rcp_f32_e32 v143, v139
	v_mul_f32_e32 v139, 0xbfb8aa3b, v140
	v_exp_f32_e32 v139, v139
	s_nop 0
	v_add_f32_e32 v139, 1.0, v139
	v_rcp_f32_e32 v144, v139
	v_mul_f32_e32 v139, 0xbfb8aa3b, v141
	v_exp_f32_e32 v139, v139
	s_nop 0
	v_add_f32_e32 v139, 1.0, v139
	v_pk_mul_f32 v[140:141], v[78:79], v[138:139] op_sel_hi:[1,0]
	v_rcp_f32_e32 v145, v139
	v_mul_f32_e32 v140, 0xbfb8aa3b, v140
	v_exp_f32_e32 v140, v140
	v_pk_mul_f32 v[138:139], v[76:77], v[138:139] op_sel_hi:[1,0]
	v_add_f32_e32 v140, 1.0, v140
	v_mul_f32_e32 v138, 0xbfb8aa3b, v138
	v_mul_f32_e32 v139, 0xbfb8aa3b, v139
	v_rcp_f32_e32 v146, v140
	v_mul_f32_e32 v140, 0xbfb8aa3b, v141
	v_exp_f32_e32 v138, v138
	v_exp_f32_e32 v139, v139
	v_exp_f32_e32 v140, v140
	v_add_f32_e32 v138, 1.0, v138
	v_add_f32_e32 v139, 1.0, v139
	v_add_f32_e32 v140, 1.0, v140
	v_rcp_f32_e32 v138, v138
	v_rcp_f32_e32 v139, v139
	v_rcp_f32_e32 v147, v140
	v_lshl_add_u64 v[140:141], v[136:137], 0, v[132:133]
	v_add_co_u32_e32 v140, vcc, s0, v140
	v_cvt_pk_bf16_f32 v136, v142, v143
	v_cvt_pk_bf16_f32 v137, v144, v145
	v_cvt_pk_bf16_f32 v138, v138, v139
	v_cvt_pk_bf16_f32 v139, v146, v147
	v_addc_co_u32_e32 v141, vcc, 0, v141, vcc
	global_store_dwordx4 v[140:141], v[136:139], off offset:512
	s_nop 1
	v_pk_mul_f32 v[136:137], v[74:75], v[2:3] op_sel_hi:[1,0]
	v_pk_mul_f32 v[138:139], v[72:73], v[2:3] op_sel_hi:[1,0]
	v_mul_f32_e32 v136, 0xbfb8aa3b, v136
	v_exp_f32_e32 v136, v136
	v_mul_f32_e32 v138, 0xbfb8aa3b, v138
	v_exp_f32_e32 v138, v138
	v_add_f32_e32 v136, 1.0, v136
	v_rcp_f32_e32 v142, v136
	v_mul_f32_e32 v136, 0xbfb8aa3b, v137
	v_exp_f32_e32 v136, v136
	v_add_f32_e32 v138, 1.0, v138
	v_rcp_f32_e32 v140, v138
	v_mul_f32_e32 v138, 0xbfb8aa3b, v139
	v_add_f32_e32 v136, 1.0, v136
	v_rcp_f32_e32 v143, v136
	v_pk_mul_f32 v[136:137], v[70:71], v[2:3] op_sel_hi:[1,0]
	v_exp_f32_e32 v138, v138
	v_mul_f32_e32 v136, 0xbfb8aa3b, v136
	v_exp_f32_e32 v136, v136
	v_add_f32_e32 v138, 1.0, v138
	v_rcp_f32_e32 v141, v138
	v_pk_mul_f32 v[138:139], v[68:69], v[2:3] op_sel_hi:[1,0]
	v_add_f32_e32 v136, 1.0, v136
	v_mul_f32_e32 v2, 0xbfb8aa3b, v138
	v_mul_f32_e32 v138, 0xbfb8aa3b, v139
	v_rcp_f32_e32 v139, v136
	v_mul_f32_e32 v136, 0xbfb8aa3b, v137
	v_exp_f32_e32 v2, v2
	v_exp_f32_e32 v138, v138
	v_exp_f32_e32 v136, v136
	v_add_f32_e32 v2, 1.0, v2
	v_add_f32_e32 v138, 1.0, v138
	v_add_f32_e32 v136, 1.0, v136
	v_rcp_f32_e32 v2, v2
	v_rcp_f32_e32 v138, v138
	v_rcp_f32_e32 v144, v136
	v_lshl_add_u64 v[136:137], v[134:135], 0, v[132:133]
	v_add_co_u32_e32 v136, vcc, s0, v136
	v_cvt_pk_bf16_f32 v132, v140, v141
	v_cvt_pk_bf16_f32 v133, v142, v143
	v_cvt_pk_bf16_f32 v134, v2, v138
	v_cvt_pk_bf16_f32 v135, v139, v144
	v_addc_co_u32_e32 v137, vcc, 0, v137, vcc
	global_store_dwordx4 v[136:137], v[132:135], off offset:512

.LBB0_71:
	s_andn2_b64 vcc, exec, s[0:1]
	s_cbranch_vccnz .LBB0_74
	s_lshl_b32 s0, s48, 8
	s_add_i32 s0, s0, s31
	v_or_b32_e32 v134, s0, v181
	v_ashrrev_i32_e32 v135, 31, v134
	v_lshl_add_u64 v[142:143], v[134:135], 2, s[70:71]
	v_mov_b32_e32 v144, v164
	v_mov_b32_e32 v146, v165
	v_mov_b32_e32 v138, v166
	v_mov_b32_e32 v136, v167
	s_or_b32 s1, s74, s49
	v_or_b32_e32 v2, s1, v242
	s_add_i32 s3, s1, 0xfffff180
	s_add_i32 s4, s0, 0xffffc000
	v_bitop3_b32 v140, s1, 56, v242 bitop3:0xc8
	s_ashr_i32 s1, s3, 6
	v_add_u32_e32 v2, 0xfffff184, v2
	s_ashr_i32 s3, s0, 11
	v_bitop3_b32 v135, s0, v250, v181 bitop3:0xc8
	s_lshr_b32 s4, s4, 4
	v_ashrrev_i32_e32 v139, 6, v2
	v_add_u32_e32 v2, 0x80, v135
	v_mov_b32_e32 v135, s3
	v_mov_b32_e32 v145, s4
	v_cmp_gt_i32_e32 vcc, s20, v134
	v_mov_b64_e32 v[132:133], s[92:93]
	v_or_b32_e32 v137, 4, v140
	v_cndmask_b32_e32 v142, v145, v135, vcc
	v_lshlrev_b32_e32 v143, 1, v142
	v_add_u32_e32 v142, s1, v143
	v_add_u32_e32 v148, v143, v139
	v_ashrrev_i32_e32 v143, 31, v142
	v_lshlrev_b64 v[142:143], 6, v[142:143]
	v_or_b32_e32 v142, v142, v140
	v_cndmask_b32_e32 v2, v244, v2, vcc
	v_ashrrev_i32_e32 v149, 31, v148
	v_mad_u64_u32 v[150:151], s[4:5], v142, s89, v[132:133]
	v_lshlrev_b32_e32 v2, 1, v2
	v_lshlrev_b64 v[148:149], 6, v[148:149]
	v_mad_i32_i24 v151, v143, s89, v151
	v_or_b32_e32 v145, v148, v137
	v_lshl_add_u64 v[142:143], v[150:151], 0, v[2:3]
	s_movk_i32 s17, 0x1000
	v_mad_u64_u32 v[152:153], s[4:5], v145, s89, v[132:133]
	v_add_co_u32_e32 v150, vcc, s17, v142
	v_mad_i32_i24 v153, v149, s89, v153
	s_nop 0
	v_addc_co_u32_e32 v151, vcc, 0, v143, vcc
	s_movk_i32 s16, 0x2000
	v_lshl_add_u64 v[148:149], v[152:153], 0, v[2:3]
	v_add_co_u32_e32 v152, vcc, s16, v142
	s_movk_i32 s21, 0x3000
	s_nop 0
	v_addc_co_u32_e32 v153, vcc, 0, v143, vcc
	v_add_co_u32_e32 v154, vcc, s21, v142
	s_movk_i32 s3, 0x7df
	s_nop 0
	v_addc_co_u32_e32 v155, vcc, 0, v143, vcc
	v_add_co_u32_e32 v156, vcc, s17, v148
	v_or_b32_e32 v141, 16, v134
	s_nop 0
	v_addc_co_u32_e32 v157, vcc, 0, v149, vcc
	v_add_co_u32_e32 v158, vcc, s16, v148
	v_or_b32_e32 v188, 32, v134
	s_nop 0
	v_addc_co_u32_e32 v159, vcc, 0, v149, vcc
	v_or_b32_e32 v189, 48, v134
	v_pk_mul_f32 v[162:163], v[128:129], v[144:145] op_sel_hi:[1,0]
	v_pk_mul_f32 v[160:161], v[130:131], v[144:145] op_sel_hi:[1,0]
	v_pk_mul_f32 v[168:169], v[126:127], v[144:145] op_sel_hi:[1,0]
	v_pk_mul_f32 v[144:145], v[124:125], v[144:145] op_sel_hi:[1,0]
	v_cvt_pk_bf16_f32 v2, v162, s0
	v_cvt_pk_bf16_f32 v147, v163, s0
	v_cvt_pk_bf16_f32 v160, v160, s0
	v_cvt_pk_bf16_f32 v161, v161, s0
	v_cvt_pk_bf16_f32 v144, v144, s0
	v_cvt_pk_bf16_f32 v145, v145, s0
	v_cvt_pk_bf16_f32 v162, v168, s0
	global_store_short v[142:143], v2, off
	global_store_short v[150:151], v147, off offset:256
	global_store_short v[152:153], v160, off offset:512
	global_store_short v[154:155], v161, off offset:768
	global_store_short v[148:149], v144, off
	global_store_short v[156:157], v145, off offset:256
	global_store_short v[158:159], v162, off offset:512
	v_add_co_u32_e32 v142, vcc, s21, v148
	v_bitop3_b32 v2, v134, s3, 16 bitop3:0xc8
	s_add_i32 s3, s0, 0xffffc010
	v_cvt_pk_bf16_f32 v163, v169, s0
	v_addc_co_u32_e32 v143, vcc, 0, v149, vcc
	s_lshr_b32 s3, s3, 4
	global_store_short v[142:143], v163, off offset:768
	v_pk_mul_f32 v[142:143], v[122:123], v[146:147] op_sel_hi:[1,0]
	v_pk_mul_f32 v[144:145], v[120:121], v[146:147] op_sel_hi:[1,0]
	v_mov_b32_e32 v147, s3
	v_cmp_gt_i32_e32 vcc, s20, v141
	v_add_u32_e32 v2, 0x80, v2
	v_cvt_pk_bf16_f32 v144, v144, s0
	v_cndmask_b32_e32 v141, v147, v135, vcc
	v_lshlrev_b32_e32 v141, 1, v141
	v_add_u32_e32 v148, s1, v141
	v_ashrrev_i32_e32 v149, 31, v148
	v_lshlrev_b64 v[148:149], 6, v[148:149]
	v_or_b32_e32 v147, v148, v140
	v_cndmask_b32_e32 v2, v244, v2, vcc
	v_mad_u64_u32 v[150:151], s[4:5], v147, s89, v[132:133]
	v_mad_i32_i24 v151, v149, s89, v151
	v_lshlrev_b32_e32 v2, 1, v2
	v_lshl_add_u64 v[148:149], v[150:151], 0, v[2:3]
	global_store_short v[148:149], v144, off
	v_add_co_u32_e32 v144, vcc, s17, v148
	v_cvt_pk_bf16_f32 v147, v145, s0
	s_nop 0
	v_addc_co_u32_e32 v145, vcc, 0, v149, vcc
	global_store_short v[144:145], v147, off offset:256
	v_add_co_u32_e32 v144, vcc, s16, v148
	v_cvt_pk_bf16_f32 v142, v142, s0
	s_nop 0
	v_addc_co_u32_e32 v145, vcc, 0, v149, vcc
	global_store_short v[144:145], v142, off offset:512
	v_add_co_u32_e32 v142, vcc, s21, v148
	v_cvt_pk_bf16_f32 v144, v143, s0
	s_nop 0
	v_addc_co_u32_e32 v143, vcc, 0, v149, vcc
	global_store_short v[142:143], v144, off offset:768
	v_pk_mul_f32 v[142:143], v[118:119], v[146:147] op_sel_hi:[1,0]
	v_pk_mul_f32 v[144:145], v[116:117], v[146:147] op_sel_hi:[1,0]
	v_add_u32_e32 v146, v141, v139
	v_ashrrev_i32_e32 v147, 31, v146
	v_lshlrev_b64 v[146:147], 6, v[146:147]
	v_or_b32_e32 v141, v146, v137
	v_mad_u64_u32 v[148:149], s[4:5], v141, s89, v[132:133]
	v_mad_i32_i24 v149, v147, s89, v149
	v_lshl_add_u64 v[146:147], v[148:149], 0, v[2:3]
	v_cvt_pk_bf16_f32 v2, v144, s0
	v_add_co_u32_e32 v144, vcc, s17, v146
	global_store_short v[146:147], v2, off
	v_cvt_pk_bf16_f32 v2, v145, s0
	v_addc_co_u32_e32 v145, vcc, 0, v147, vcc
	global_store_short v[144:145], v2, off offset:256
	v_add_co_u32_e32 v144, vcc, s16, v146
	v_cvt_pk_bf16_f32 v2, v142, s0
	s_nop 0
	v_addc_co_u32_e32 v145, vcc, 0, v147, vcc
	v_add_co_u32_e32 v142, vcc, s21, v146
	global_store_short v[144:145], v2, off offset:512
	v_cvt_pk_bf16_f32 v2, v143, s0
	v_addc_co_u32_e32 v143, vcc, 0, v147, vcc
	s_movk_i32 s3, 0x7ef
	global_store_short v[142:143], v2, off offset:768
	v_bitop3_b32 v2, v134, s3, 32 bitop3:0xc8
	s_add_i32 s3, s0, 0xffffc020
	s_lshr_b32 s3, s3, 4
	v_mov_b32_e32 v141, s3
	v_cmp_gt_i32_e32 vcc, s20, v188
	v_add_u32_e32 v2, 0x80, v2
	v_pk_mul_f32 v[144:145], v[112:113], v[138:139] op_sel_hi:[1,0]
	v_cndmask_b32_e32 v141, v141, v135, vcc
	v_lshlrev_b32_e32 v141, 1, v141
	v_add_u32_e32 v146, s1, v141
	v_ashrrev_i32_e32 v147, 31, v146
	v_lshlrev_b64 v[146:147], 6, v[146:147]
	v_or_b32_e32 v146, v146, v140
	v_cndmask_b32_e32 v2, v244, v2, vcc
	v_mad_u64_u32 v[148:149], s[4:5], v146, s89, v[132:133]
	v_mad_i32_i24 v149, v147, s89, v149
	v_lshlrev_b32_e32 v2, 1, v2
	v_lshl_add_u64 v[146:147], v[148:149], 0, v[2:3]
	v_cvt_pk_bf16_f32 v144, v144, s0
	global_store_short v[146:147], v144, off
	v_add_co_u32_e32 v144, vcc, s17, v146
	v_cvt_pk_bf16_f32 v148, v145, s0
	s_nop 0
	v_addc_co_u32_e32 v145, vcc, 0, v147, vcc
	v_pk_mul_f32 v[142:143], v[114:115], v[138:139] op_sel_hi:[1,0]
	global_store_short v[144:145], v148, off offset:256
	v_add_co_u32_e32 v144, vcc, s16, v146
	v_cvt_pk_bf16_f32 v142, v142, s0
	s_nop 0
	v_addc_co_u32_e32 v145, vcc, 0, v147, vcc
	global_store_short v[144:145], v142, off offset:512
	v_add_co_u32_e32 v142, vcc, s21, v146
	v_add_u32_e32 v146, v141, v139
	v_cvt_pk_bf16_f32 v144, v143, s0
	v_addc_co_u32_e32 v143, vcc, 0, v147, vcc
	v_ashrrev_i32_e32 v147, 31, v146
	v_lshlrev_b64 v[146:147], 6, v[146:147]
	global_store_short v[142:143], v144, off offset:768
	v_pk_mul_f32 v[142:143], v[110:111], v[138:139] op_sel_hi:[1,0]
	v_pk_mul_f32 v[144:145], v[108:109], v[138:139] op_sel_hi:[1,0]
	v_or_b32_e32 v138, v146, v137
	v_mad_u64_u32 v[148:149], s[4:5], v138, s89, v[132:133]
	v_mad_i32_i24 v149, v147, s89, v149
	v_lshl_add_u64 v[146:147], v[148:149], 0, v[2:3]
	v_cvt_pk_bf16_f32 v2, v144, s0
	v_add_co_u32_e32 v144, vcc, s17, v146
	global_store_short v[146:147], v2, off
	v_cvt_pk_bf16_f32 v2, v145, s0
	v_addc_co_u32_e32 v145, vcc, 0, v147, vcc
	global_store_short v[144:145], v2, off offset:256
	v_add_co_u32_e32 v144, vcc, s16, v146
	v_cvt_pk_bf16_f32 v2, v142, s0
	s_nop 0
	v_addc_co_u32_e32 v145, vcc, 0, v147, vcc
	v_add_co_u32_e32 v142, vcc, s21, v146
	global_store_short v[144:145], v2, off offset:512
	v_cvt_pk_bf16_f32 v2, v143, s0
	v_addc_co_u32_e32 v143, vcc, 0, v147, vcc
	s_movk_i32 s3, 0x7ff
	global_store_short v[142:143], v2, off offset:768
	v_bitop3_b32 v2, v134, s3, 48 bitop3:0xc8
	s_add_i32 s3, s0, 0xffffc030
	s_lshr_b32 s3, s3, 4
	v_mov_b32_e32 v134, s3
	v_cmp_gt_i32_e32 vcc, s20, v189
	v_add_u32_e32 v2, 0x80, v2
	v_pk_mul_f32 v[144:145], v[104:105], v[136:137] op_sel_hi:[1,0]
	v_cndmask_b32_e32 v134, v134, v135, vcc
	v_lshlrev_b32_e32 v138, 1, v134
	v_add_u32_e32 v134, s1, v138
	v_ashrrev_i32_e32 v135, 31, v134
	v_lshlrev_b64 v[134:135], 6, v[134:135]
	v_or_b32_e32 v134, v134, v140
	v_cndmask_b32_e32 v2, v244, v2, vcc
	v_mad_u64_u32 v[146:147], s[4:5], v134, s89, v[132:133]
	v_mad_i32_i24 v147, v135, s89, v147
	v_lshlrev_b32_e32 v2, 1, v2
	v_lshl_add_u64 v[134:135], v[146:147], 0, v[2:3]
	v_cvt_pk_bf16_f32 v141, v144, s0
	v_add_co_u32_e32 v144, vcc, s17, v134
	global_store_short v[134:135], v141, off
	v_cvt_pk_bf16_f32 v141, v145, s0
	v_addc_co_u32_e32 v145, vcc, 0, v135, vcc
	v_pk_mul_f32 v[142:143], v[106:107], v[136:137] op_sel_hi:[1,0]
	global_store_short v[144:145], v141, off offset:256
	v_add_co_u32_e32 v144, vcc, s16, v134
	v_cvt_pk_bf16_f32 v141, v142, s0
	s_nop 0
	v_addc_co_u32_e32 v145, vcc, 0, v135, vcc
	global_store_short v[144:145], v141, off offset:512
	v_add_u32_e32 v144, v138, v139
	v_add_co_u32_e32 v134, vcc, s21, v134
	v_ashrrev_i32_e32 v145, 31, v144
	v_cvt_pk_bf16_f32 v141, v143, s0
	v_addc_co_u32_e32 v135, vcc, 0, v135, vcc
	v_lshlrev_b64 v[144:145], 6, v[144:145]
	global_store_short v[134:135], v141, off offset:768
	v_pk_mul_f32 v[134:135], v[102:103], v[136:137] op_sel_hi:[1,0]
	v_pk_mul_f32 v[142:143], v[100:101], v[136:137] op_sel_hi:[1,0]
	v_or_b32_e32 v136, v144, v137
	v_mad_u64_u32 v[132:133], s[4:5], v136, s89, v[132:133]
	v_mad_i32_i24 v133, v145, s89, v133
	v_lshl_add_u64 v[132:133], v[132:133], 0, v[2:3]
	v_cvt_pk_bf16_f32 v2, v142, s0
	v_add_co_u32_e32 v142, vcc, 0x1000, v132
	global_store_short v[132:133], v2, off
	v_cvt_pk_bf16_f32 v2, v143, s0
	v_addc_co_u32_e32 v143, vcc, 0, v133, vcc
	global_store_short v[142:143], v2, off offset:256
	v_add_co_u32_e32 v142, vcc, 0x2000, v132
	v_cvt_pk_bf16_f32 v2, v134, s0
	s_nop 0
	v_addc_co_u32_e32 v143, vcc, 0, v133, vcc
	v_add_co_u32_e32 v132, vcc, 0x3000, v132
	global_store_short v[142:143], v2, off offset:512
	v_cvt_pk_bf16_f32 v2, v135, s0
	v_addc_co_u32_e32 v133, vcc, 0, v133, vcc
	s_cmp_eq_u32 s48, 64
	global_store_short v[132:133], v2, off offset:768
	s_cbranch_scc1 .LBB0_74
	s_add_i32 s3, s0, 0x80
	v_or_b32_e32 v134, s3, v181
	v_ashrrev_i32_e32 v135, 31, v134
	v_lshl_add_u64 v[142:143], v[134:135], 2, s[70:71]
	v_mov_b32_e32 v138, v246
	v_mov_b32_e32 v144, v247
	s_add_i32 s4, s0, 0xffffc080
	s_ashr_i32 s5, s3, 11
	v_bitop3_b32 v2, s3, v250, v181 bitop3:0xc8
	s_lshr_b32 s3, s4, 4
	v_mov_b32_e32 v136, s3
	v_mov_b32_e32 v197, s5
	v_cmp_gt_i32_e32 vcc, s20, v134
	v_mov_b64_e32 v[132:133], s[92:93]
	v_add_u32_e32 v2, 0x80, v2
	v_cndmask_b32_e32 v147, v136, v197, vcc
	v_mov_b32_e32 v146, v248
	v_mov_b32_e32 v136, v249
	v_lshlrev_b32_e32 v143, 1, v147
	v_add_u32_e32 v142, s1, v143
	v_add_u32_e32 v148, v143, v139
	v_ashrrev_i32_e32 v143, 31, v142
	v_lshlrev_b64 v[142:143], 6, v[142:143]
	v_or_b32_e32 v142, v142, v140
	v_cndmask_b32_e32 v2, v244, v2, vcc
	v_ashrrev_i32_e32 v149, 31, v148
	v_mad_u64_u32 v[150:151], s[4:5], v142, s89, v[132:133]
	v_lshlrev_b32_e32 v2, 1, v2
	v_lshlrev_b64 v[148:149], 6, v[148:149]
	v_mad_i32_i24 v151, v143, s89, v151
	v_or_b32_e32 v147, v148, v137
	v_lshl_add_u64 v[142:143], v[150:151], 0, v[2:3]
	v_mad_u64_u32 v[152:153], s[4:5], v147, s89, v[132:133]
	v_add_co_u32_e32 v150, vcc, s17, v142
	v_mad_i32_i24 v153, v149, s89, v153
	s_nop 0
	v_addc_co_u32_e32 v151, vcc, 0, v143, vcc
	v_lshl_add_u64 v[148:149], v[152:153], 0, v[2:3]
	v_add_co_u32_e32 v152, vcc, s16, v142
	s_movk_i32 s3, 0x7df
	s_nop 0
	v_addc_co_u32_e32 v153, vcc, 0, v143, vcc
	v_add_co_u32_e32 v154, vcc, s21, v142
	v_bitop3_b32 v145, v134, s3, 16 bitop3:0xc8
	s_nop 0
	v_addc_co_u32_e32 v155, vcc, 0, v143, vcc
	v_add_co_u32_e32 v156, vcc, s17, v148
	s_add_i32 s3, s0, 0xffffc090
	s_nop 0
	v_addc_co_u32_e32 v157, vcc, 0, v149, vcc
	v_add_co_u32_e32 v158, vcc, s16, v148
	v_or_b32_e32 v135, 16, v134
	s_nop 0
	v_addc_co_u32_e32 v159, vcc, 0, v149, vcc
	v_add_co_u32_e32 v160, vcc, s21, v148
	s_lshr_b32 s3, s3, 4
	s_nop 0
	v_addc_co_u32_e32 v161, vcc, 0, v149, vcc
	v_cmp_gt_i32_e32 vcc, s20, v135
	v_or_b32_e32 v141, 32, v134
	v_or_b32_e32 v196, 48, v134
	v_pk_mul_f32 v[168:169], v[96:97], v[138:139] op_sel_hi:[1,0]
	v_pk_mul_f32 v[162:163], v[98:99], v[138:139] op_sel_hi:[1,0]
	v_pk_mul_f32 v[188:189], v[94:95], v[138:139] op_sel_hi:[1,0]
	v_pk_mul_f32 v[190:191], v[92:93], v[138:139] op_sel_hi:[1,0]
	v_cvt_pk_bf16_f32 v2, v168, s0
	v_cvt_pk_bf16_f32 v138, v169, s0
	v_cvt_pk_bf16_f32 v147, v162, s0
	v_cvt_pk_bf16_f32 v162, v163, s0
	v_cvt_pk_bf16_f32 v163, v190, s0
	v_cvt_pk_bf16_f32 v168, v191, s0
	v_cvt_pk_bf16_f32 v169, v188, s0
	v_cvt_pk_bf16_f32 v188, v189, s0
	global_store_short v[142:143], v2, off
	global_store_short v[150:151], v138, off offset:256
	global_store_short v[152:153], v147, off offset:512
	global_store_short v[154:155], v162, off offset:768
	global_store_short v[148:149], v163, off
	global_store_short v[156:157], v168, off offset:256
	global_store_short v[158:159], v169, off offset:512
	global_store_short v[160:161], v188, off offset:768
	v_mov_b32_e32 v138, s3
	v_cndmask_b32_e32 v135, v138, v197, vcc
	v_lshlrev_b32_e32 v135, 1, v135
	v_add_u32_e32 v142, s1, v135
	v_ashrrev_i32_e32 v143, 31, v142
	v_lshlrev_b64 v[142:143], 6, v[142:143]
	v_add_u32_e32 v2, 0x80, v145
	v_or_b32_e32 v138, v142, v140
	v_cndmask_b32_e32 v2, v244, v2, vcc
	v_mad_u64_u32 v[148:149], s[4:5], v138, s89, v[132:133]
	v_mad_i32_i24 v149, v143, s89, v149
	v_lshlrev_b32_e32 v2, 1, v2
	v_pk_mul_f32 v[194:195], v[88:89], v[144:145] op_sel_hi:[1,0]
	v_lshl_add_u64 v[142:143], v[148:149], 0, v[2:3]
	v_cvt_pk_bf16_f32 v138, v194, s0
	v_add_co_u32_e32 v148, vcc, s17, v142
	global_store_short v[142:143], v138, off
	v_cvt_pk_bf16_f32 v138, v195, s0
	v_addc_co_u32_e32 v149, vcc, 0, v143, vcc
	v_pk_mul_f32 v[192:193], v[90:91], v[144:145] op_sel_hi:[1,0]
	global_store_short v[148:149], v138, off offset:256
	v_add_co_u32_e32 v148, vcc, s16, v142
	v_cvt_pk_bf16_f32 v138, v192, s0
	s_nop 0
	v_addc_co_u32_e32 v149, vcc, 0, v143, vcc
	global_store_short v[148:149], v138, off offset:512
	v_add_u32_e32 v148, v135, v139
	v_ashrrev_i32_e32 v149, 31, v148
	v_lshlrev_b64 v[148:149], 6, v[148:149]
	v_or_b32_e32 v135, v148, v137
	v_add_co_u32_e32 v142, vcc, s21, v142
	v_mad_u64_u32 v[150:151], s[4:5], v135, s89, v[132:133]
	v_cvt_pk_bf16_f32 v138, v193, s0
	v_addc_co_u32_e32 v143, vcc, 0, v143, vcc
	v_mad_i32_i24 v151, v149, s89, v151
	global_store_short v[142:143], v138, off offset:768
	v_pk_mul_f32 v[142:143], v[86:87], v[144:145] op_sel_hi:[1,0]
	v_pk_mul_f32 v[144:145], v[84:85], v[144:145] op_sel_hi:[1,0]
	v_lshl_add_u64 v[148:149], v[150:151], 0, v[2:3]
	v_cvt_pk_bf16_f32 v2, v144, s0
	v_add_co_u32_e32 v144, vcc, s17, v148
	global_store_short v[148:149], v2, off
	v_cvt_pk_bf16_f32 v2, v145, s0
	v_addc_co_u32_e32 v145, vcc, 0, v149, vcc
	global_store_short v[144:145], v2, off offset:256
	v_add_co_u32_e32 v144, vcc, s16, v148
	v_cvt_pk_bf16_f32 v2, v142, s0
	s_nop 0
	v_addc_co_u32_e32 v145, vcc, 0, v149, vcc
	v_add_co_u32_e32 v142, vcc, s21, v148
	global_store_short v[144:145], v2, off offset:512
	v_cvt_pk_bf16_f32 v2, v143, s0
	v_addc_co_u32_e32 v143, vcc, 0, v149, vcc
	s_movk_i32 s3, 0x7ef
	global_store_short v[142:143], v2, off offset:768
	v_bitop3_b32 v2, v134, s3, 32 bitop3:0xc8
	s_add_i32 s3, s0, 0xffffc0a0
	s_lshr_b32 s3, s3, 4
	v_mov_b32_e32 v135, s3
	v_cmp_gt_i32_e32 vcc, s20, v141
	v_add_u32_e32 v2, 0x80, v2
	v_pk_mul_f32 v[144:145], v[80:81], v[146:147] op_sel_hi:[1,0]
	v_cndmask_b32_e32 v135, v135, v197, vcc
	v_lshlrev_b32_e32 v135, 1, v135
	v_add_u32_e32 v148, s1, v135
	v_ashrrev_i32_e32 v149, 31, v148
	v_lshlrev_b64 v[148:149], 6, v[148:149]
	v_or_b32_e32 v138, v148, v140
	v_cndmask_b32_e32 v2, v244, v2, vcc
	v_mad_u64_u32 v[150:151], s[4:5], v138, s89, v[132:133]
	v_mad_i32_i24 v151, v149, s89, v151
	v_lshlrev_b32_e32 v2, 1, v2
	v_lshl_add_u64 v[148:149], v[150:151], 0, v[2:3]
	v_cvt_pk_bf16_f32 v138, v144, s0
	v_add_co_u32_e32 v144, vcc, s17, v148
	global_store_short v[148:149], v138, off
	v_cvt_pk_bf16_f32 v138, v145, s0
	v_addc_co_u32_e32 v145, vcc, 0, v149, vcc
	global_store_short v[144:145], v138, off offset:256
	v_add_co_u32_e32 v144, vcc, s16, v148
	v_pk_mul_f32 v[142:143], v[82:83], v[146:147] op_sel_hi:[1,0]
	s_nop 0
	v_addc_co_u32_e32 v145, vcc, 0, v149, vcc
	v_cvt_pk_bf16_f32 v138, v142, s0
	v_add_co_u32_e32 v142, vcc, s21, v148
	global_store_short v[144:145], v138, off offset:512
	v_cvt_pk_bf16_f32 v138, v143, s0
	v_addc_co_u32_e32 v143, vcc, 0, v149, vcc
	global_store_short v[142:143], v138, off offset:768
	v_pk_mul_f32 v[142:143], v[78:79], v[146:147] op_sel_hi:[1,0]
	v_pk_mul_f32 v[144:145], v[76:77], v[146:147] op_sel_hi:[1,0]
	v_add_u32_e32 v146, v135, v139
	v_ashrrev_i32_e32 v147, 31, v146
	v_lshlrev_b64 v[146:147], 6, v[146:147]
	v_or_b32_e32 v135, v146, v137
	v_mad_u64_u32 v[148:149], s[4:5], v135, s89, v[132:133]
	v_mad_i32_i24 v149, v147, s89, v149
	v_lshl_add_u64 v[146:147], v[148:149], 0, v[2:3]
	v_cvt_pk_bf16_f32 v2, v144, s0
	v_add_co_u32_e32 v144, vcc, s17, v146
	global_store_short v[146:147], v2, off
	v_cvt_pk_bf16_f32 v2, v145, s0
	v_addc_co_u32_e32 v145, vcc, 0, v147, vcc
	global_store_short v[144:145], v2, off offset:256
	v_add_co_u32_e32 v144, vcc, s16, v146
	v_cvt_pk_bf16_f32 v2, v142, s0
	s_nop 0
	v_addc_co_u32_e32 v145, vcc, 0, v147, vcc
	global_store_short v[144:145], v2, off offset:512
	v_cvt_pk_bf16_f32 v2, v143, s0
	v_add_co_u32_e32 v142, vcc, s21, v146
	s_addk_i32 s0, 0xc0b0
	s_nop 0
	v_addc_co_u32_e32 v143, vcc, 0, v147, vcc
	s_movk_i32 s3, 0x7ff
	s_lshr_b32 s0, s0, 4
	global_store_short v[142:143], v2, off offset:768
	v_bitop3_b32 v2, v134, s3, 48 bitop3:0xc8
	v_mov_b32_e32 v134, s0
	v_cmp_gt_i32_e32 vcc, s20, v196
	v_add_u32_e32 v2, 0x80, v2
	v_pk_mul_f32 v[144:145], v[72:73], v[136:137] op_sel_hi:[1,0]
	v_cndmask_b32_e32 v134, v134, v197, vcc
	v_lshlrev_b32_e32 v138, 1, v134
	v_add_u32_e32 v134, s1, v138
	v_ashrrev_i32_e32 v135, 31, v134
	v_lshlrev_b64 v[134:135], 6, v[134:135]
	v_or_b32_e32 v134, v134, v140
	v_cndmask_b32_e32 v2, v244, v2, vcc
	v_mad_u64_u32 v[140:141], s[0:1], v134, s89, v[132:133]
	v_mad_i32_i24 v141, v135, s89, v141
	v_lshlrev_b32_e32 v2, 1, v2
	v_lshl_add_u64 v[134:135], v[140:141], 0, v[2:3]
	v_cvt_pk_bf16_f32 v140, v144, s0
	global_store_short v[134:135], v140, off
	v_add_co_u32_e32 v140, vcc, s17, v134
	v_cvt_pk_bf16_f32 v144, v145, s0
	s_nop 0
	v_addc_co_u32_e32 v141, vcc, 0, v135, vcc
	global_store_short v[140:141], v144, off offset:256
	v_add_co_u32_e32 v140, vcc, s16, v134
	v_pk_mul_f32 v[142:143], v[74:75], v[136:137] op_sel_hi:[1,0]
	s_nop 0
	v_addc_co_u32_e32 v141, vcc, 0, v135, vcc
	v_add_u32_e32 v138, v138, v139
	v_cvt_pk_bf16_f32 v142, v142, s0
	v_add_co_u32_e32 v134, vcc, s21, v134
	v_ashrrev_i32_e32 v139, 31, v138
	global_store_short v[140:141], v142, off offset:512
	v_cvt_pk_bf16_f32 v140, v143, s0
	v_addc_co_u32_e32 v135, vcc, 0, v135, vcc
	v_lshlrev_b64 v[138:139], 6, v[138:139]
	global_store_short v[134:135], v140, off offset:768
	v_pk_mul_f32 v[134:135], v[70:71], v[136:137] op_sel_hi:[1,0]
	v_pk_mul_f32 v[140:141], v[68:69], v[136:137] op_sel_hi:[1,0]
	v_or_b32_e32 v136, v138, v137
	v_mad_u64_u32 v[132:133], s[0:1], v136, s89, v[132:133]
	v_mad_i32_i24 v133, v139, s89, v133
	v_lshl_add_u64 v[132:133], v[132:133], 0, v[2:3]
	v_cvt_pk_bf16_f32 v2, v140, s0
	v_add_co_u32_e32 v136, vcc, 0x1000, v132
	global_store_short v[132:133], v2, off
	v_cvt_pk_bf16_f32 v2, v141, s0
	v_addc_co_u32_e32 v137, vcc, 0, v133, vcc
	global_store_short v[136:137], v2, off offset:256
	v_add_co_u32_e32 v136, vcc, 0x2000, v132
	v_cvt_pk_bf16_f32 v2, v134, s0
	s_nop 0
	v_addc_co_u32_e32 v137, vcc, 0, v133, vcc
	v_add_co_u32_e32 v132, vcc, 0x3000, v132
	global_store_short v[136:137], v2, off offset:512
	v_cvt_pk_bf16_f32 v2, v135, s0
	v_addc_co_u32_e32 v133, vcc, 0, v133, vcc
	global_store_short v[132:133], v2, off offset:768

.LBB0_148:
	s_andn2_b64 vcc, exec, s[0:1]
	s_cbranch_vccnz .LBB0_166
	s_cmp_lt_i32 s2, 2
	s_mov_b64 s[0:1], -1
	s_cbranch_scc1 .LBB0_158
	s_cmp_gt_i32 s2, 2
	s_cbranch_scc0 .LBB0_154
	s_lshl_b32 s0, s48, 8
	v_add_u32_e32 v134, s0, v241
	v_ashrrev_i32_e32 v135, 31, v134
	v_lshl_add_u64 v[146:147], v[134:135], 2, s[70:71]
	v_mov_b32_e32 v148, v164
	v_mov_b32_e32 v144, v165
	v_mov_b32_e32 v140, v166
	v_mov_b32_e32 v2, v167
	v_or_b32_e32 v132, s74, v178
	v_ashrrev_i32_e32 v133, 31, v132
	v_lshlrev_b64 v[132:133], 1, v[132:133]
	s_mov_b32 s0, 0x643f000
	v_or_b32_e32 v142, 16, v134
	v_ashrrev_i32_e32 v143, 31, v142
	v_lshlrev_b64 v[142:143], 11, v[142:143]
	v_lshl_add_u64 v[142:143], s[94:95], 0, v[142:143]
	v_or_b32_e32 v138, 32, v134
	v_ashrrev_i32_e32 v139, 31, v138
	v_lshlrev_b64 v[138:139], 11, v[138:139]
	v_lshl_add_u64 v[138:139], s[94:95], 0, v[138:139]
	v_or_b32_e32 v136, 48, v134
	v_ashrrev_i32_e32 v137, 31, v136
	v_lshlrev_b64 v[136:137], 11, v[136:137]
	v_lshl_add_u64 v[136:137], s[94:95], 0, v[136:137]
	s_cmp_eq_u32 s48, 64
	v_pk_mul_f32 v[146:147], v[128:129], v[148:149] op_sel_hi:[1,0]
	s_nop 0
	v_mul_f32_e32 v141, 0xbfb8aa3b, v146
	v_exp_f32_e32 v141, v141
	v_pk_mul_f32 v[150:151], v[130:131], v[148:149] op_sel_hi:[1,0]
	v_add_f32_e32 v141, 1.0, v141
	v_rcp_f32_e32 v152, v141
	v_mul_f32_e32 v141, 0xbfb8aa3b, v147
	v_exp_f32_e32 v141, v141
	s_nop 0
	v_add_f32_e32 v141, 1.0, v141
	v_rcp_f32_e32 v153, v141
	v_mul_f32_e32 v141, 0xbfb8aa3b, v150
	v_exp_f32_e32 v141, v141
	v_pk_mul_f32 v[146:147], v[146:147], v[152:153]
	s_nop 0
	v_cvt_pk_bf16_f32 v146, v146, v147
	v_add_f32_e32 v141, 1.0, v141
	v_rcp_f32_e32 v152, v141
	v_mul_f32_e32 v141, 0xbfb8aa3b, v151
	v_exp_f32_e32 v141, v141
	s_nop 0
	v_add_f32_e32 v141, 1.0, v141
	v_rcp_f32_e32 v153, v141
	s_nop 0
	v_pk_mul_f32 v[150:151], v[150:151], v[152:153]
	v_pk_mul_f32 v[152:153], v[126:127], v[148:149] op_sel_hi:[1,0]
	v_pk_mul_f32 v[148:149], v[124:125], v[148:149] op_sel_hi:[1,0]
	v_cvt_pk_bf16_f32 v147, v150, v151
	v_mul_f32_e32 v141, 0xbfb8aa3b, v148
	v_exp_f32_e32 v141, v141
	s_nop 0
	v_add_f32_e32 v141, 1.0, v141
	v_rcp_f32_e32 v154, v141
	v_mul_f32_e32 v141, 0xbfb8aa3b, v149
	v_exp_f32_e32 v141, v141
	s_nop 0
	v_add_f32_e32 v141, 1.0, v141
	v_rcp_f32_e32 v155, v141
	v_mul_f32_e32 v141, 0xbfb8aa3b, v152
	v_exp_f32_e32 v141, v141
	v_pk_mul_f32 v[148:149], v[148:149], v[154:155]
	s_nop 0
	v_cvt_pk_bf16_f32 v148, v148, v149
	v_add_f32_e32 v141, 1.0, v141
	v_rcp_f32_e32 v154, v141
	v_mul_f32_e32 v141, 0xbfb8aa3b, v153
	v_exp_f32_e32 v141, v141
	s_nop 0
	v_add_f32_e32 v141, 1.0, v141
	v_rcp_f32_e32 v155, v141
	s_nop 0
	v_pk_mul_f32 v[152:153], v[152:153], v[154:155]
	v_lshlrev_b64 v[154:155], 11, v[134:135]
	v_lshl_add_u64 v[154:155], s[94:95], 0, v[154:155]
	v_lshl_add_u64 v[154:155], v[154:155], 0, v[132:133]
	v_add_co_u32_e32 v150, vcc, s0, v154
	v_cvt_pk_bf16_f32 v149, v152, v153
	s_nop 0
	v_addc_co_u32_e32 v151, vcc, 0, v155, vcc
	global_store_dwordx4 v[150:151], v[146:149], off
	s_nop 1
	v_pk_mul_f32 v[146:147], v[120:121], v[144:145] op_sel_hi:[1,0]
	v_pk_mul_f32 v[148:149], v[122:123], v[144:145] op_sel_hi:[1,0]
	v_mul_f32_e32 v135, 0xbfb8aa3b, v146
	v_exp_f32_e32 v135, v135
	s_nop 0
	v_add_f32_e32 v135, 1.0, v135
	v_rcp_f32_e32 v150, v135
	v_mul_f32_e32 v135, 0xbfb8aa3b, v147
	v_exp_f32_e32 v135, v135
	s_nop 0
	v_add_f32_e32 v135, 1.0, v135
	v_rcp_f32_e32 v151, v135
	v_mul_f32_e32 v135, 0xbfb8aa3b, v148
	v_exp_f32_e32 v135, v135
	v_pk_mul_f32 v[146:147], v[146:147], v[150:151]
	v_add_f32_e32 v135, 1.0, v135
	v_rcp_f32_e32 v150, v135
	v_mul_f32_e32 v135, 0xbfb8aa3b, v149
	v_exp_f32_e32 v135, v135
	s_nop 0
	v_add_f32_e32 v135, 1.0, v135
	v_rcp_f32_e32 v151, v135
	s_nop 0
	v_pk_mul_f32 v[148:149], v[148:149], v[150:151]
	v_pk_mul_f32 v[150:151], v[118:119], v[144:145] op_sel_hi:[1,0]
	v_pk_mul_f32 v[144:145], v[116:117], v[144:145] op_sel_hi:[1,0]
	s_nop 0
	v_mul_f32_e32 v135, 0xbfb8aa3b, v144
	v_exp_f32_e32 v135, v135
	s_nop 0
	v_add_f32_e32 v135, 1.0, v135
	v_rcp_f32_e32 v152, v135
	v_mul_f32_e32 v135, 0xbfb8aa3b, v145
	v_exp_f32_e32 v135, v135
	s_nop 0
	v_add_f32_e32 v135, 1.0, v135
	v_rcp_f32_e32 v153, v135
	v_mul_f32_e32 v135, 0xbfb8aa3b, v150
	v_exp_f32_e32 v135, v135
	v_pk_mul_f32 v[144:145], v[144:145], v[152:153]
	s_nop 0
	v_cvt_pk_bf16_f32 v144, v144, v145
	v_add_f32_e32 v135, 1.0, v135
	v_rcp_f32_e32 v152, v135
	v_mul_f32_e32 v135, 0xbfb8aa3b, v151
	v_exp_f32_e32 v135, v135
	s_nop 0
	v_add_f32_e32 v135, 1.0, v135
	v_rcp_f32_e32 v153, v135
	s_nop 0
	v_pk_mul_f32 v[150:151], v[150:151], v[152:153]
	v_lshl_add_u64 v[152:153], v[142:143], 0, v[132:133]
	v_cvt_pk_bf16_f32 v142, v146, v147
	v_add_co_u32_e32 v146, vcc, s0, v152
	v_cvt_pk_bf16_f32 v143, v148, v149
	v_cvt_pk_bf16_f32 v145, v150, v151
	v_addc_co_u32_e32 v147, vcc, 0, v153, vcc
	global_store_dwordx4 v[146:147], v[142:145], off
	s_nop 1
	v_pk_mul_f32 v[144:145], v[112:113], v[140:141] op_sel_hi:[1,0]
	v_pk_mul_f32 v[142:143], v[114:115], v[140:141] op_sel_hi:[1,0]
	v_mul_f32_e32 v135, 0xbfb8aa3b, v144
	v_exp_f32_e32 v135, v135
	s_nop 0
	v_add_f32_e32 v135, 1.0, v135
	v_rcp_f32_e32 v146, v135
	v_mul_f32_e32 v135, 0xbfb8aa3b, v145
	v_exp_f32_e32 v135, v135
	s_nop 0
	v_add_f32_e32 v135, 1.0, v135
	v_rcp_f32_e32 v147, v135
	v_mul_f32_e32 v135, 0xbfb8aa3b, v142
	v_exp_f32_e32 v135, v135
	v_pk_mul_f32 v[144:145], v[144:145], v[146:147]
	v_add_f32_e32 v135, 1.0, v135
	v_rcp_f32_e32 v146, v135
	v_mul_f32_e32 v135, 0xbfb8aa3b, v143
	v_exp_f32_e32 v135, v135
	s_nop 0
	v_add_f32_e32 v135, 1.0, v135
	v_rcp_f32_e32 v147, v135
	s_nop 0
	v_pk_mul_f32 v[142:143], v[142:143], v[146:147]
	v_pk_mul_f32 v[146:147], v[110:111], v[140:141] op_sel_hi:[1,0]
	v_pk_mul_f32 v[140:141], v[108:109], v[140:141] op_sel_hi:[1,0]
	s_nop 0
	v_mul_f32_e32 v135, 0xbfb8aa3b, v140
	v_exp_f32_e32 v135, v135
	s_nop 0
	v_add_f32_e32 v135, 1.0, v135
	v_rcp_f32_e32 v148, v135
	v_mul_f32_e32 v135, 0xbfb8aa3b, v141
	v_exp_f32_e32 v135, v135
	s_nop 0
	v_add_f32_e32 v135, 1.0, v135
	v_rcp_f32_e32 v149, v135
	v_mul_f32_e32 v135, 0xbfb8aa3b, v146
	v_exp_f32_e32 v135, v135
	v_pk_mul_f32 v[140:141], v[140:141], v[148:149]
	s_nop 0
	v_cvt_pk_bf16_f32 v140, v140, v141
	v_add_f32_e32 v135, 1.0, v135
	v_rcp_f32_e32 v148, v135
	v_mul_f32_e32 v135, 0xbfb8aa3b, v147
	v_exp_f32_e32 v135, v135
	s_nop 0
	v_add_f32_e32 v135, 1.0, v135
	v_rcp_f32_e32 v149, v135
	s_nop 0
	v_pk_mul_f32 v[146:147], v[146:147], v[148:149]
	v_lshl_add_u64 v[148:149], v[138:139], 0, v[132:133]
	v_cvt_pk_bf16_f32 v139, v142, v143
	v_add_co_u32_e32 v142, vcc, s0, v148
	v_cvt_pk_bf16_f32 v138, v144, v145
	v_cvt_pk_bf16_f32 v141, v146, v147
	v_addc_co_u32_e32 v143, vcc, 0, v149, vcc
	global_store_dwordx4 v[142:143], v[138:141], off
	v_pk_mul_f32 v[144:145], v[100:101], v[2:3] op_sel_hi:[1,0]
	s_nop 0
	v_pk_mul_f32 v[140:141], v[104:105], v[2:3] op_sel_hi:[1,0]
	v_pk_mul_f32 v[138:139], v[106:107], v[2:3] op_sel_hi:[1,0]
	v_mul_f32_e32 v135, 0xbfb8aa3b, v140
	v_exp_f32_e32 v135, v135
	s_nop 0
	v_add_f32_e32 v135, 1.0, v135
	v_rcp_f32_e32 v142, v135
	v_mul_f32_e32 v135, 0xbfb8aa3b, v141
	v_exp_f32_e32 v135, v135
	s_nop 0
	v_add_f32_e32 v135, 1.0, v135
	v_rcp_f32_e32 v143, v135
	v_mul_f32_e32 v135, 0xbfb8aa3b, v138
	v_exp_f32_e32 v135, v135
	v_pk_mul_f32 v[140:141], v[140:141], v[142:143]
	v_add_f32_e32 v135, 1.0, v135
	v_rcp_f32_e32 v142, v135
	v_mul_f32_e32 v135, 0xbfb8aa3b, v139
	v_exp_f32_e32 v135, v135
	s_nop 0
	v_add_f32_e32 v135, 1.0, v135
	v_rcp_f32_e32 v143, v135
	s_nop 0
	v_pk_mul_f32 v[138:139], v[138:139], v[142:143]
	v_pk_mul_f32 v[142:143], v[102:103], v[2:3] op_sel_hi:[1,0]
	v_mul_f32_e32 v2, 0xbfb8aa3b, v144
	v_exp_f32_e32 v2, v2
	s_nop 0
	v_add_f32_e32 v2, 1.0, v2
	v_rcp_f32_e32 v146, v2
	v_mul_f32_e32 v2, 0xbfb8aa3b, v145
	v_exp_f32_e32 v2, v2
	s_nop 0
	v_add_f32_e32 v2, 1.0, v2
	v_rcp_f32_e32 v147, v2
	v_mul_f32_e32 v2, 0xbfb8aa3b, v142
	v_exp_f32_e32 v2, v2
	v_pk_mul_f32 v[144:145], v[144:145], v[146:147]
	v_add_f32_e32 v2, 1.0, v2
	v_rcp_f32_e32 v146, v2
	v_mul_f32_e32 v2, 0xbfb8aa3b, v143
	v_exp_f32_e32 v2, v2
	s_nop 0
	v_add_f32_e32 v2, 1.0, v2
	v_rcp_f32_e32 v147, v2
	s_nop 0
	v_pk_mul_f32 v[142:143], v[142:143], v[146:147]
	v_lshl_add_u64 v[146:147], v[136:137], 0, v[132:133]
	v_cvt_pk_bf16_f32 v136, v140, v141
	v_add_co_u32_e32 v140, vcc, 0x643f000, v146
	v_cvt_pk_bf16_f32 v137, v138, v139
	v_cvt_pk_bf16_f32 v138, v144, v145
	v_cvt_pk_bf16_f32 v139, v142, v143
	v_addc_co_u32_e32 v141, vcc, 0, v147, vcc
	global_store_dwordx4 v[140:141], v[136:139], off
	s_cbranch_scc1 .LBB0_153
	v_add_u32_e32 v142, 0x80, v134
	v_ashrrev_i32_e32 v143, 31, v142
	v_lshl_add_u64 v[144:145], v[142:143], 2, s[70:71]
	v_mov_b32_e32 v148, v246
	v_mov_b32_e32 v146, v247
	v_mov_b32_e32 v138, v248
	v_mov_b32_e32 v2, v249
	v_lshlrev_b64 v[142:143], 11, v[142:143]
	v_lshl_add_u64 v[142:143], s[94:95], 0, v[142:143]
	v_add_u32_e32 v140, 0x90, v134
	v_ashrrev_i32_e32 v141, 31, v140
	v_lshlrev_b64 v[140:141], 11, v[140:141]
	v_lshl_add_u64 v[140:141], s[94:95], 0, v[140:141]
	v_add_u32_e32 v136, 0xa0, v134
	v_ashrrev_i32_e32 v137, 31, v136
	v_lshlrev_b64 v[136:137], 11, v[136:137]
	v_lshl_add_u64 v[136:137], s[94:95], 0, v[136:137]
	v_add_u32_e32 v134, 0xb0, v134
	v_ashrrev_i32_e32 v135, 31, v134
	v_lshlrev_b64 v[134:135], 11, v[134:135]
	v_lshl_add_u64 v[134:135], s[94:95], 0, v[134:135]
	v_pk_mul_f32 v[150:151], v[96:97], v[148:149] op_sel_hi:[1,0]
	s_nop 0
	v_mul_f32_e32 v139, 0xbfb8aa3b, v150
	v_exp_f32_e32 v139, v139
	v_pk_mul_f32 v[144:145], v[98:99], v[148:149] op_sel_hi:[1,0]
	v_add_f32_e32 v139, 1.0, v139
	v_rcp_f32_e32 v152, v139
	v_mul_f32_e32 v139, 0xbfb8aa3b, v151
	v_exp_f32_e32 v139, v139
	s_nop 0
	v_add_f32_e32 v139, 1.0, v139
	v_rcp_f32_e32 v153, v139
	v_mul_f32_e32 v139, 0xbfb8aa3b, v144
	v_exp_f32_e32 v139, v139
	v_pk_mul_f32 v[150:151], v[150:151], v[152:153]
	v_add_f32_e32 v139, 1.0, v139
	v_rcp_f32_e32 v152, v139
	v_mul_f32_e32 v139, 0xbfb8aa3b, v145
	v_exp_f32_e32 v139, v139
	s_nop 0
	v_add_f32_e32 v139, 1.0, v139
	v_rcp_f32_e32 v153, v139
	s_nop 0
	v_pk_mul_f32 v[144:145], v[144:145], v[152:153]
	v_pk_mul_f32 v[152:153], v[94:95], v[148:149] op_sel_hi:[1,0]
	v_pk_mul_f32 v[148:149], v[92:93], v[148:149] op_sel_hi:[1,0]
	s_nop 0
	v_mul_f32_e32 v139, 0xbfb8aa3b, v148
	v_exp_f32_e32 v139, v139
	s_nop 0
	v_add_f32_e32 v139, 1.0, v139
	v_rcp_f32_e32 v154, v139
	v_mul_f32_e32 v139, 0xbfb8aa3b, v149
	v_exp_f32_e32 v139, v139
	s_nop 0
	v_add_f32_e32 v139, 1.0, v139
	v_rcp_f32_e32 v155, v139
	v_mul_f32_e32 v139, 0xbfb8aa3b, v152
	v_exp_f32_e32 v139, v139
	v_pk_mul_f32 v[148:149], v[148:149], v[154:155]
	v_add_f32_e32 v139, 1.0, v139
	v_rcp_f32_e32 v154, v139
	v_mul_f32_e32 v139, 0xbfb8aa3b, v153
	v_exp_f32_e32 v139, v139
	s_nop 0
	v_add_f32_e32 v139, 1.0, v139
	v_rcp_f32_e32 v155, v139
	s_nop 0
	v_pk_mul_f32 v[152:153], v[152:153], v[154:155]
	v_lshl_add_u64 v[154:155], v[142:143], 0, v[132:133]
	v_cvt_pk_bf16_f32 v143, v144, v145
	v_cvt_pk_bf16_f32 v144, v148, v149
	v_add_co_u32_e32 v148, vcc, s0, v154
	v_cvt_pk_bf16_f32 v142, v150, v151
	v_cvt_pk_bf16_f32 v145, v152, v153
	v_addc_co_u32_e32 v149, vcc, 0, v155, vcc
	global_store_dwordx4 v[148:149], v[142:145], off
	s_nop 1
	v_pk_mul_f32 v[142:143], v[88:89], v[146:147] op_sel_hi:[1,0]
	v_pk_mul_f32 v[144:145], v[90:91], v[146:147] op_sel_hi:[1,0]
	v_mul_f32_e32 v139, 0xbfb8aa3b, v142
	v_exp_f32_e32 v139, v139
	s_nop 0
	v_add_f32_e32 v139, 1.0, v139
	v_rcp_f32_e32 v148, v139
	v_mul_f32_e32 v139, 0xbfb8aa3b, v143
	v_exp_f32_e32 v139, v139
	s_nop 0
	v_add_f32_e32 v139, 1.0, v139
	v_rcp_f32_e32 v149, v139
	v_mul_f32_e32 v139, 0xbfb8aa3b, v144
	v_exp_f32_e32 v139, v139
	v_pk_mul_f32 v[142:143], v[142:143], v[148:149]
	v_add_f32_e32 v139, 1.0, v139
	v_rcp_f32_e32 v148, v139
	v_mul_f32_e32 v139, 0xbfb8aa3b, v145
	v_exp_f32_e32 v139, v139
	s_nop 0
	v_add_f32_e32 v139, 1.0, v139
	v_rcp_f32_e32 v149, v139
	s_nop 0
	v_pk_mul_f32 v[144:145], v[144:145], v[148:149]
	v_pk_mul_f32 v[148:149], v[86:87], v[146:147] op_sel_hi:[1,0]
	v_pk_mul_f32 v[146:147], v[84:85], v[146:147] op_sel_hi:[1,0]
	s_nop 0
	v_mul_f32_e32 v139, 0xbfb8aa3b, v146
	v_exp_f32_e32 v139, v139
	s_nop 0
	v_add_f32_e32 v139, 1.0, v139
	v_rcp_f32_e32 v150, v139
	v_mul_f32_e32 v139, 0xbfb8aa3b, v147
	v_exp_f32_e32 v139, v139
	s_nop 0
	v_add_f32_e32 v139, 1.0, v139
	v_rcp_f32_e32 v151, v139
	v_mul_f32_e32 v139, 0xbfb8aa3b, v148
	v_exp_f32_e32 v139, v139
	v_pk_mul_f32 v[146:147], v[146:147], v[150:151]
	v_add_f32_e32 v139, 1.0, v139
	v_rcp_f32_e32 v150, v139
	v_mul_f32_e32 v139, 0xbfb8aa3b, v149
	v_exp_f32_e32 v139, v139
	s_nop 0
	v_add_f32_e32 v139, 1.0, v139
	v_rcp_f32_e32 v151, v139
	s_nop 0
	v_pk_mul_f32 v[148:149], v[148:149], v[150:151]
	v_lshl_add_u64 v[150:151], v[140:141], 0, v[132:133]
	v_cvt_pk_bf16_f32 v141, v144, v145
	v_add_co_u32_e32 v144, vcc, s0, v150
	v_cvt_pk_bf16_f32 v140, v142, v143
	v_cvt_pk_bf16_f32 v142, v146, v147
	v_cvt_pk_bf16_f32 v143, v148, v149
	v_addc_co_u32_e32 v145, vcc, 0, v151, vcc
	global_store_dwordx4 v[144:145], v[140:143], off
	s_nop 1
	v_pk_mul_f32 v[142:143], v[80:81], v[138:139] op_sel_hi:[1,0]
	v_pk_mul_f32 v[140:141], v[82:83], v[138:139] op_sel_hi:[1,0]
	v_mul_f32_e32 v139, 0xbfb8aa3b, v142
	v_exp_f32_e32 v139, v139
	s_nop 0
	v_add_f32_e32 v139, 1.0, v139
	v_rcp_f32_e32 v144, v139
	v_mul_f32_e32 v139, 0xbfb8aa3b, v143
	v_exp_f32_e32 v139, v139
	s_nop 0
	v_add_f32_e32 v139, 1.0, v139
	v_rcp_f32_e32 v145, v139
	v_mul_f32_e32 v139, 0xbfb8aa3b, v140
	v_exp_f32_e32 v139, v139
	v_pk_mul_f32 v[142:143], v[142:143], v[144:145]
	v_add_f32_e32 v139, 1.0, v139
	v_rcp_f32_e32 v144, v139
	v_mul_f32_e32 v139, 0xbfb8aa3b, v141
	v_exp_f32_e32 v139, v139
	s_nop 0
	v_add_f32_e32 v139, 1.0, v139
	v_rcp_f32_e32 v145, v139
	s_nop 0
	v_pk_mul_f32 v[140:141], v[140:141], v[144:145]
	v_pk_mul_f32 v[144:145], v[78:79], v[138:139] op_sel_hi:[1,0]
	v_pk_mul_f32 v[138:139], v[76:77], v[138:139] op_sel_hi:[1,0]
	s_nop 0
	v_mul_f32_e32 v146, 0xbfb8aa3b, v138
	v_mul_f32_e32 v147, 0xbfb8aa3b, v139
	v_exp_f32_e32 v146, v146
	v_exp_f32_e32 v147, v147
	v_add_f32_e32 v146, 1.0, v146
	v_add_f32_e32 v147, 1.0, v147
	v_rcp_f32_e32 v146, v146
	v_rcp_f32_e32 v147, v147
	s_nop 0
	v_pk_mul_f32 v[138:139], v[138:139], v[146:147]
	v_mul_f32_e32 v146, 0xbfb8aa3b, v144
	v_mul_f32_e32 v147, 0xbfb8aa3b, v145
	v_exp_f32_e32 v146, v146
	v_exp_f32_e32 v147, v147
	v_cvt_pk_bf16_f32 v138, v138, v139
	v_add_f32_e32 v146, 1.0, v146
	v_add_f32_e32 v147, 1.0, v147
	v_rcp_f32_e32 v146, v146
	v_rcp_f32_e32 v147, v147
	s_nop 0
	v_pk_mul_f32 v[144:145], v[144:145], v[146:147]
	v_lshl_add_u64 v[146:147], v[136:137], 0, v[132:133]
	v_cvt_pk_bf16_f32 v137, v140, v141
	v_add_co_u32_e32 v140, vcc, s0, v146
	v_cvt_pk_bf16_f32 v136, v142, v143
	v_cvt_pk_bf16_f32 v139, v144, v145
	v_addc_co_u32_e32 v141, vcc, 0, v147, vcc
	global_store_dwordx4 v[140:141], v[136:139], off
	v_pk_mul_f32 v[142:143], v[68:69], v[2:3] op_sel_hi:[1,0]
	s_nop 0
	v_pk_mul_f32 v[138:139], v[72:73], v[2:3] op_sel_hi:[1,0]
	v_pk_mul_f32 v[136:137], v[74:75], v[2:3] op_sel_hi:[1,0]
	v_mul_f32_e32 v140, 0xbfb8aa3b, v138
	v_mul_f32_e32 v141, 0xbfb8aa3b, v139
	v_exp_f32_e32 v140, v140
	v_exp_f32_e32 v141, v141
	v_add_f32_e32 v140, 1.0, v140
	v_add_f32_e32 v141, 1.0, v141
	v_rcp_f32_e32 v140, v140
	v_rcp_f32_e32 v141, v141
	s_nop 0
	v_pk_mul_f32 v[138:139], v[138:139], v[140:141]
	v_mul_f32_e32 v140, 0xbfb8aa3b, v136
	v_mul_f32_e32 v141, 0xbfb8aa3b, v137
	v_exp_f32_e32 v140, v140
	v_exp_f32_e32 v141, v141
	v_add_f32_e32 v140, 1.0, v140
	v_add_f32_e32 v141, 1.0, v141
	v_rcp_f32_e32 v140, v140
	v_rcp_f32_e32 v141, v141
	s_nop 0
	v_pk_mul_f32 v[136:137], v[136:137], v[140:141]
	v_pk_mul_f32 v[140:141], v[70:71], v[2:3] op_sel_hi:[1,0]
	v_mul_f32_e32 v2, 0xbfb8aa3b, v142
	v_exp_f32_e32 v2, v2
	s_nop 0
	v_add_f32_e32 v2, 1.0, v2
	v_rcp_f32_e32 v144, v2
	v_mul_f32_e32 v2, 0xbfb8aa3b, v143
	v_exp_f32_e32 v2, v2
	s_nop 0
	v_add_f32_e32 v2, 1.0, v2
	v_rcp_f32_e32 v145, v2
	v_mul_f32_e32 v2, 0xbfb8aa3b, v140
	v_exp_f32_e32 v2, v2
	v_pk_mul_f32 v[142:143], v[142:143], v[144:145]
	v_add_f32_e32 v2, 1.0, v2
	v_rcp_f32_e32 v144, v2
	v_mul_f32_e32 v2, 0xbfb8aa3b, v141
	v_exp_f32_e32 v2, v2
	s_nop 0
	v_add_f32_e32 v2, 1.0, v2
	v_rcp_f32_e32 v145, v2
	s_nop 0
	v_pk_mul_f32 v[140:141], v[140:141], v[144:145]
	v_lshl_add_u64 v[144:145], v[134:135], 0, v[132:133]
	v_cvt_pk_bf16_f32 v133, v136, v137
	v_add_co_u32_e32 v136, vcc, 0x643f000, v144
	v_cvt_pk_bf16_f32 v132, v138, v139
	v_cvt_pk_bf16_f32 v134, v142, v143
	v_cvt_pk_bf16_f32 v135, v140, v141
	v_addc_co_u32_e32 v137, vcc, 0, v145, vcc
	global_store_dwordx4 v[136:137], v[132:135], off

.Lsec78_b:
	s_lshl_b32 s2, s48, 8
	v_add_u32_e32 v70, s2, v241
	v_ashrrev_i32_e32 v71, 31, v70
	v_lshl_add_u64 v[68:69], v[70:71], 2, s[70:71]
	v_mov_b32_e32 v82, v164
	v_mov_b32_e32 v80, v165
	v_mov_b32_e32 v76, v166
	v_mov_b32_e32 v2, v167
	s_ashr_i32 s75, s74, 31
	s_mov_b32 s2, 0x9ce6000
	s_cmp_eq_u32 s17, 8
	s_cselect_b32 s2, 0xbd25800, s2
	v_or_b32_e32 v78, 16, v70
	v_ashrrev_i32_e32 v79, 31, v78
	v_lshlrev_b64 v[78:79], 11, v[78:79]
	v_lshl_add_u64 v[78:79], s[94:95], 0, v[78:79]
	v_or_b32_e32 v74, 32, v70
	v_ashrrev_i32_e32 v75, 31, v74
	v_lshlrev_b64 v[74:75], 11, v[74:75]
	v_lshl_add_u64 v[74:75], s[94:95], 0, v[74:75]
	v_or_b32_e32 v72, 48, v70
	v_ashrrev_i32_e32 v73, 31, v72
	v_lshlrev_b64 v[72:73], 11, v[72:73]
	v_lshl_add_u64 v[72:73], s[94:95], 0, v[72:73]
	s_cmp_eq_u32 s48, 64
	v_pk_mul_f32 v[68:69], v[66:67], v[82:83] op_sel_hi:[1,0]
	s_nop 0
	v_mul_f32_e32 v68, 0xbfb8aa3b, v68
	v_exp_f32_e32 v68, v68
	v_pk_mul_f32 v[84:85], v[64:65], v[82:83] op_sel_hi:[1,0]
	v_add_f32_e32 v68, 1.0, v68
	v_mul_f32_e32 v77, 0xbfb8aa3b, v84
	v_rcp_f32_e32 v84, v68
	v_mul_f32_e32 v68, 0xbfb8aa3b, v69
	v_exp_f32_e32 v68, v68
	v_mul_f32_e32 v81, 0xbfb8aa3b, v85
	v_exp_f32_e32 v77, v77
	v_exp_f32_e32 v81, v81
	v_add_f32_e32 v68, 1.0, v68
	v_rcp_f32_e32 v85, v68
	v_pk_mul_f32 v[68:69], v[62:63], v[82:83] op_sel_hi:[1,0]
	v_pk_mul_f32 v[82:83], v[60:61], v[82:83] op_sel_hi:[1,0]
	v_mul_f32_e32 v68, 0xbfb8aa3b, v68
	v_mul_f32_e32 v82, 0xbfb8aa3b, v82
	v_exp_f32_e32 v68, v68
	v_exp_f32_e32 v82, v82
	v_add_f32_e32 v77, 1.0, v77
	v_add_f32_e32 v81, 1.0, v81
	v_add_f32_e32 v68, 1.0, v68
	v_add_f32_e32 v82, 1.0, v82
	v_rcp_f32_e32 v90, v68
	v_mul_f32_e32 v68, 0xbfb8aa3b, v69
	v_rcp_f32_e32 v88, v82
	v_mul_f32_e32 v82, 0xbfb8aa3b, v83
	v_exp_f32_e32 v68, v68
	v_exp_f32_e32 v82, v82
	v_rcp_f32_e32 v77, v77
	v_rcp_f32_e32 v81, v81
	v_add_f32_e32 v68, 1.0, v68
	v_add_f32_e32 v82, 1.0, v82
	v_rcp_f32_e32 v91, v68
	v_lshlrev_b64 v[68:69], 11, v[70:71]
	v_rcp_f32_e32 v89, v82
	v_lshl_add_u64 v[82:83], s[94:95], 0, v[68:69]
	v_lshl_add_u64 v[68:69], s[74:75], 0, v[178:179]
	v_lshlrev_b64 v[68:69], 1, v[68:69]
	v_lshl_add_u64 v[86:87], v[82:83], 0, v[68:69]
	v_add_co_u32_e32 v86, vcc, s2, v86
	v_cvt_pk_bf16_f32 v82, v77, v81
	v_cvt_pk_bf16_f32 v83, v84, v85
	v_cvt_pk_bf16_f32 v84, v88, v89
	v_cvt_pk_bf16_f32 v85, v90, v91
	v_addc_co_u32_e32 v87, vcc, 0, v87, vcc
	global_store_dwordx4 v[86:87], v[82:85], off offset:768
	s_nop 1
	v_pk_mul_f32 v[82:83], v[58:59], v[80:81] op_sel_hi:[1,0]
	v_pk_mul_f32 v[84:85], v[56:57], v[80:81] op_sel_hi:[1,0]
	v_mul_f32_e32 v81, 0xbfb8aa3b, v82
	v_exp_f32_e32 v81, v81
	v_mul_f32_e32 v71, 0xbfb8aa3b, v84
	v_mul_f32_e32 v77, 0xbfb8aa3b, v85
	v_exp_f32_e32 v71, v71
	v_add_f32_e32 v81, 1.0, v81
	v_rcp_f32_e32 v84, v81
	v_mul_f32_e32 v81, 0xbfb8aa3b, v83
	v_exp_f32_e32 v81, v81
	v_exp_f32_e32 v77, v77
	v_add_f32_e32 v71, 1.0, v71
	v_rcp_f32_e32 v71, v71
	v_add_f32_e32 v81, 1.0, v81
	v_pk_mul_f32 v[82:83], v[54:55], v[80:81] op_sel_hi:[1,0]
	v_rcp_f32_e32 v85, v81
	v_mul_f32_e32 v82, 0xbfb8aa3b, v82
	v_exp_f32_e32 v82, v82
	v_pk_mul_f32 v[80:81], v[52:53], v[80:81] op_sel_hi:[1,0]
	v_add_f32_e32 v77, 1.0, v77
	v_mul_f32_e32 v80, 0xbfb8aa3b, v80
	v_add_f32_e32 v82, 1.0, v82
	v_mul_f32_e32 v81, 0xbfb8aa3b, v81
	v_rcp_f32_e32 v86, v82
	v_mul_f32_e32 v82, 0xbfb8aa3b, v83
	v_exp_f32_e32 v80, v80
	v_exp_f32_e32 v81, v81
	v_exp_f32_e32 v82, v82
	v_rcp_f32_e32 v77, v77
	v_add_f32_e32 v80, 1.0, v80
	v_add_f32_e32 v81, 1.0, v81
	v_add_f32_e32 v82, 1.0, v82
	v_rcp_f32_e32 v80, v80
	v_rcp_f32_e32 v81, v81
	v_rcp_f32_e32 v87, v82
	v_lshl_add_u64 v[82:83], v[78:79], 0, v[68:69]
	v_add_co_u32_e32 v82, vcc, s2, v82
	v_cvt_pk_bf16_f32 v78, v71, v77
	v_cvt_pk_bf16_f32 v79, v84, v85
	v_cvt_pk_bf16_f32 v80, v80, v81
	v_cvt_pk_bf16_f32 v81, v86, v87
	v_addc_co_u32_e32 v83, vcc, 0, v83, vcc
	global_store_dwordx4 v[82:83], v[78:81], off offset:768
	s_nop 1
	v_pk_mul_f32 v[80:81], v[48:49], v[76:77] op_sel_hi:[1,0]
	v_pk_mul_f32 v[78:79], v[50:51], v[76:77] op_sel_hi:[1,0]
	v_mul_f32_e32 v77, 0xbfb8aa3b, v81
	v_exp_f32_e32 v77, v77
	v_mul_f32_e32 v71, 0xbfb8aa3b, v80
	v_exp_f32_e32 v71, v71
	v_add_f32_e32 v77, 1.0, v77
	v_rcp_f32_e32 v80, v77
	v_mul_f32_e32 v77, 0xbfb8aa3b, v78
	v_exp_f32_e32 v77, v77
	v_add_f32_e32 v71, 1.0, v71
	v_rcp_f32_e32 v71, v71
	v_add_f32_e32 v77, 1.0, v77
	v_rcp_f32_e32 v81, v77
	v_mul_f32_e32 v77, 0xbfb8aa3b, v79
	v_exp_f32_e32 v77, v77
	s_nop 0
	v_add_f32_e32 v77, 1.0, v77
	v_pk_mul_f32 v[78:79], v[46:47], v[76:77] op_sel_hi:[1,0]
	v_rcp_f32_e32 v82, v77
	v_mul_f32_e32 v78, 0xbfb8aa3b, v78
	v_exp_f32_e32 v78, v78
	v_pk_mul_f32 v[76:77], v[44:45], v[76:77] op_sel_hi:[1,0]
	v_add_f32_e32 v78, 1.0, v78
	v_mul_f32_e32 v76, 0xbfb8aa3b, v76
	v_mul_f32_e32 v77, 0xbfb8aa3b, v77
	v_rcp_f32_e32 v83, v78
	v_mul_f32_e32 v78, 0xbfb8aa3b, v79
	v_exp_f32_e32 v76, v76
	v_exp_f32_e32 v77, v77
	v_exp_f32_e32 v78, v78
	v_add_f32_e32 v76, 1.0, v76
	v_add_f32_e32 v77, 1.0, v77
	v_add_f32_e32 v78, 1.0, v78
	v_rcp_f32_e32 v76, v76
	v_rcp_f32_e32 v77, v77
	v_rcp_f32_e32 v84, v78
	v_lshl_add_u64 v[78:79], v[74:75], 0, v[68:69]
	v_add_co_u32_e32 v78, vcc, s2, v78
	v_cvt_pk_bf16_f32 v74, v71, v80
	v_cvt_pk_bf16_f32 v75, v81, v82
	v_cvt_pk_bf16_f32 v76, v76, v77
	v_cvt_pk_bf16_f32 v77, v83, v84
	v_addc_co_u32_e32 v79, vcc, 0, v79, vcc
	global_store_dwordx4 v[78:79], v[74:77], off offset:768
	s_nop 1
	v_pk_mul_f32 v[74:75], v[42:43], v[2:3] op_sel_hi:[1,0]
	v_pk_mul_f32 v[76:77], v[40:41], v[2:3] op_sel_hi:[1,0]
	v_mul_f32_e32 v74, 0xbfb8aa3b, v74
	v_exp_f32_e32 v74, v74
	v_mul_f32_e32 v71, 0xbfb8aa3b, v76
	v_mul_f32_e32 v76, 0xbfb8aa3b, v77
	v_exp_f32_e32 v76, v76
	v_add_f32_e32 v74, 1.0, v74
	v_rcp_f32_e32 v79, v74
	v_mul_f32_e32 v74, 0xbfb8aa3b, v75
	v_exp_f32_e32 v74, v74
	v_add_f32_e32 v76, 1.0, v76
	v_rcp_f32_e32 v78, v76
	v_pk_mul_f32 v[76:77], v[36:37], v[2:3] op_sel_hi:[1,0]
	v_add_f32_e32 v74, 1.0, v74
	v_rcp_f32_e32 v80, v74
	v_pk_mul_f32 v[74:75], v[38:39], v[2:3] op_sel_hi:[1,0]
	v_mul_f32_e32 v2, 0xbfb8aa3b, v76
	v_mul_f32_e32 v74, 0xbfb8aa3b, v74
	v_exp_f32_e32 v74, v74
	v_mul_f32_e32 v76, 0xbfb8aa3b, v77
	v_exp_f32_e32 v71, v71
	v_exp_f32_e32 v2, v2
	v_add_f32_e32 v74, 1.0, v74
	v_rcp_f32_e32 v82, v74
	v_mul_f32_e32 v74, 0xbfb8aa3b, v75
	v_exp_f32_e32 v76, v76
	v_exp_f32_e32 v74, v74
	v_add_f32_e32 v71, 1.0, v71
	v_add_f32_e32 v2, 1.0, v2
	v_add_f32_e32 v76, 1.0, v76
	v_add_f32_e32 v74, 1.0, v74
	v_rcp_f32_e32 v71, v71
	v_rcp_f32_e32 v2, v2
	v_rcp_f32_e32 v81, v76
	v_rcp_f32_e32 v75, v74
	v_lshl_add_u64 v[76:77], v[72:73], 0, v[68:69]
	v_add_co_u32_e32 v76, vcc, s2, v76
	v_cvt_pk_bf16_f32 v72, v71, v78
	v_cvt_pk_bf16_f32 v73, v79, v80
	v_cvt_pk_bf16_f32 v74, v2, v81
	v_cvt_pk_bf16_f32 v75, v82, v75
	v_addc_co_u32_e32 v77, vcc, 0, v77, vcc
	global_store_dwordx4 v[76:77], v[72:75], off offset:768
	s_cbranch_scc1 .LBB0_176
	v_add_u32_e32 v80, 0x80, v70
	v_ashrrev_i32_e32 v81, 31, v80
	v_lshl_add_u64 v[82:83], v[80:81], 2, s[70:71]
	v_mov_b32_e32 v84, v246
	v_mov_b32_e32 v78, v247
	v_mov_b32_e32 v74, v248
	v_mov_b32_e32 v2, v249
	v_lshlrev_b64 v[80:81], 11, v[80:81]
	v_lshl_add_u64 v[80:81], s[94:95], 0, v[80:81]
	v_add_u32_e32 v76, 0x90, v70
	v_ashrrev_i32_e32 v77, 31, v76
	v_lshlrev_b64 v[76:77], 11, v[76:77]
	v_lshl_add_u64 v[76:77], s[94:95], 0, v[76:77]
	v_add_u32_e32 v72, 0xa0, v70
	v_ashrrev_i32_e32 v73, 31, v72
	v_lshlrev_b64 v[72:73], 11, v[72:73]
	v_lshl_add_u64 v[72:73], s[94:95], 0, v[72:73]
	v_add_u32_e32 v70, 0xb0, v70
	v_ashrrev_i32_e32 v71, 31, v70
	v_lshlrev_b64 v[70:71], 11, v[70:71]
	v_lshl_add_u64 v[70:71], s[94:95], 0, v[70:71]
	v_pk_mul_f32 v[82:83], v[34:35], v[84:85] op_sel_hi:[1,0]
	s_nop 0
	v_mul_f32_e32 v82, 0xbfb8aa3b, v82
	v_exp_f32_e32 v82, v82
	v_pk_mul_f32 v[86:87], v[32:33], v[84:85] op_sel_hi:[1,0]
	v_add_f32_e32 v82, 1.0, v82
	v_mul_f32_e32 v75, 0xbfb8aa3b, v86
	v_rcp_f32_e32 v86, v82
	v_mul_f32_e32 v82, 0xbfb8aa3b, v83
	v_exp_f32_e32 v82, v82
	v_mul_f32_e32 v79, 0xbfb8aa3b, v87
	v_exp_f32_e32 v75, v75
	v_exp_f32_e32 v79, v79
	v_add_f32_e32 v82, 1.0, v82
	v_rcp_f32_e32 v87, v82
	v_pk_mul_f32 v[82:83], v[30:31], v[84:85] op_sel_hi:[1,0]
	v_pk_mul_f32 v[84:85], v[28:29], v[84:85] op_sel_hi:[1,0]
	v_mul_f32_e32 v82, 0xbfb8aa3b, v82
	v_mul_f32_e32 v84, 0xbfb8aa3b, v84
	v_exp_f32_e32 v84, v84
	v_exp_f32_e32 v82, v82
	v_add_f32_e32 v75, 1.0, v75
	v_add_f32_e32 v79, 1.0, v79
	v_add_f32_e32 v84, 1.0, v84
	v_add_f32_e32 v82, 1.0, v82
	v_rcp_f32_e32 v88, v84
	v_mul_f32_e32 v84, 0xbfb8aa3b, v85
	v_rcp_f32_e32 v90, v82
	v_mul_f32_e32 v82, 0xbfb8aa3b, v83
	v_exp_f32_e32 v84, v84
	v_exp_f32_e32 v82, v82
	v_rcp_f32_e32 v75, v75
	v_rcp_f32_e32 v79, v79
	v_add_f32_e32 v84, 1.0, v84
	v_add_f32_e32 v82, 1.0, v82
	v_rcp_f32_e32 v89, v84
	v_rcp_f32_e32 v83, v82
	v_lshl_add_u64 v[84:85], v[80:81], 0, v[68:69]
	v_add_co_u32_e32 v84, vcc, s2, v84
	v_cvt_pk_bf16_f32 v80, v75, v79
	v_cvt_pk_bf16_f32 v81, v86, v87
	v_cvt_pk_bf16_f32 v82, v88, v89
	v_cvt_pk_bf16_f32 v83, v90, v83
	v_addc_co_u32_e32 v85, vcc, 0, v85, vcc
	global_store_dwordx4 v[84:85], v[80:83], off offset:768
	s_nop 1
	v_pk_mul_f32 v[82:83], v[24:25], v[78:79] op_sel_hi:[1,0]
	v_pk_mul_f32 v[80:81], v[26:27], v[78:79] op_sel_hi:[1,0]
	v_mul_f32_e32 v79, 0xbfb8aa3b, v83
	v_exp_f32_e32 v79, v79
	v_mul_f32_e32 v75, 0xbfb8aa3b, v82
	v_exp_f32_e32 v75, v75
	v_add_f32_e32 v79, 1.0, v79
	v_rcp_f32_e32 v82, v79
	v_mul_f32_e32 v79, 0xbfb8aa3b, v80
	v_exp_f32_e32 v79, v79
	v_add_f32_e32 v75, 1.0, v75
	v_rcp_f32_e32 v75, v75
	v_add_f32_e32 v79, 1.0, v79
	v_rcp_f32_e32 v83, v79
	v_mul_f32_e32 v79, 0xbfb8aa3b, v81
	v_exp_f32_e32 v79, v79
	s_nop 0
	v_add_f32_e32 v79, 1.0, v79
	v_pk_mul_f32 v[80:81], v[22:23], v[78:79] op_sel_hi:[1,0]
	v_rcp_f32_e32 v84, v79
	v_mul_f32_e32 v80, 0xbfb8aa3b, v80
	v_exp_f32_e32 v80, v80
	v_pk_mul_f32 v[78:79], v[20:21], v[78:79] op_sel_hi:[1,0]
	v_add_f32_e32 v80, 1.0, v80
	v_mul_f32_e32 v78, 0xbfb8aa3b, v78
	v_mul_f32_e32 v79, 0xbfb8aa3b, v79
	v_rcp_f32_e32 v85, v80
	v_mul_f32_e32 v80, 0xbfb8aa3b, v81
	v_exp_f32_e32 v78, v78
	v_exp_f32_e32 v79, v79
	v_exp_f32_e32 v80, v80
	v_add_f32_e32 v78, 1.0, v78
	v_add_f32_e32 v79, 1.0, v79
	v_add_f32_e32 v80, 1.0, v80
	v_rcp_f32_e32 v78, v78
	v_rcp_f32_e32 v79, v79
	v_rcp_f32_e32 v86, v80
	v_lshl_add_u64 v[80:81], v[76:77], 0, v[68:69]
	v_add_co_u32_e32 v80, vcc, s2, v80
	v_cvt_pk_bf16_f32 v76, v75, v82
	v_cvt_pk_bf16_f32 v77, v83, v84
	v_cvt_pk_bf16_f32 v78, v78, v79
	v_cvt_pk_bf16_f32 v79, v85, v86
	v_addc_co_u32_e32 v81, vcc, 0, v81, vcc
	global_store_dwordx4 v[80:81], v[76:79], off offset:768
	s_nop 1
	v_pk_mul_f32 v[78:79], v[16:17], v[74:75] op_sel_hi:[1,0]
	v_pk_mul_f32 v[76:77], v[18:19], v[74:75] op_sel_hi:[1,0]
	v_mul_f32_e32 v75, 0xbfb8aa3b, v78
	v_exp_f32_e32 v75, v75
	s_nop 0
	v_add_f32_e32 v75, 1.0, v75
	v_rcp_f32_e32 v78, v75
	v_mul_f32_e32 v75, 0xbfb8aa3b, v79
	v_exp_f32_e32 v75, v75
	s_nop 0
	v_add_f32_e32 v75, 1.0, v75
	v_rcp_f32_e32 v79, v75
	v_mul_f32_e32 v75, 0xbfb8aa3b, v76
	v_exp_f32_e32 v75, v75
	s_nop 0
	v_add_f32_e32 v75, 1.0, v75
	v_rcp_f32_e32 v80, v75
	v_mul_f32_e32 v75, 0xbfb8aa3b, v77
	v_exp_f32_e32 v75, v75
	s_nop 0
	v_add_f32_e32 v75, 1.0, v75
	v_pk_mul_f32 v[76:77], v[14:15], v[74:75] op_sel_hi:[1,0]
	v_rcp_f32_e32 v81, v75
	v_mul_f32_e32 v76, 0xbfb8aa3b, v76
	v_exp_f32_e32 v76, v76
	v_pk_mul_f32 v[74:75], v[12:13], v[74:75] op_sel_hi:[1,0]
	v_add_f32_e32 v76, 1.0, v76
	v_mul_f32_e32 v74, 0xbfb8aa3b, v74
	v_mul_f32_e32 v75, 0xbfb8aa3b, v75
	v_rcp_f32_e32 v82, v76
	v_mul_f32_e32 v76, 0xbfb8aa3b, v77
	v_exp_f32_e32 v74, v74
	v_exp_f32_e32 v75, v75
	v_exp_f32_e32 v76, v76
	v_add_f32_e32 v74, 1.0, v74
	v_add_f32_e32 v75, 1.0, v75
	v_add_f32_e32 v76, 1.0, v76
	v_rcp_f32_e32 v74, v74
	v_rcp_f32_e32 v75, v75
	v_rcp_f32_e32 v83, v76
	v_lshl_add_u64 v[76:77], v[72:73], 0, v[68:69]
	v_add_co_u32_e32 v76, vcc, s2, v76
	v_cvt_pk_bf16_f32 v72, v78, v79
	v_cvt_pk_bf16_f32 v73, v80, v81
	v_cvt_pk_bf16_f32 v74, v74, v75
	v_cvt_pk_bf16_f32 v75, v82, v83
	v_addc_co_u32_e32 v77, vcc, 0, v77, vcc
	global_store_dwordx4 v[76:77], v[72:75], off offset:768
	s_nop 1
	v_pk_mul_f32 v[72:73], v[10:11], v[2:3] op_sel_hi:[1,0]
	v_pk_mul_f32 v[74:75], v[8:9], v[2:3] op_sel_hi:[1,0]
	v_mul_f32_e32 v72, 0xbfb8aa3b, v72
	v_exp_f32_e32 v72, v72
	v_mul_f32_e32 v74, 0xbfb8aa3b, v74
	v_exp_f32_e32 v74, v74
	v_add_f32_e32 v72, 1.0, v72
	v_rcp_f32_e32 v78, v72
	v_mul_f32_e32 v72, 0xbfb8aa3b, v73
	v_exp_f32_e32 v72, v72
	v_add_f32_e32 v74, 1.0, v74
	v_rcp_f32_e32 v76, v74
	v_mul_f32_e32 v74, 0xbfb8aa3b, v75
	v_add_f32_e32 v72, 1.0, v72
	v_rcp_f32_e32 v79, v72
	v_pk_mul_f32 v[72:73], v[6:7], v[2:3] op_sel_hi:[1,0]
	v_exp_f32_e32 v74, v74
	v_mul_f32_e32 v72, 0xbfb8aa3b, v72
	v_exp_f32_e32 v72, v72
	v_add_f32_e32 v74, 1.0, v74
	v_rcp_f32_e32 v77, v74
	v_pk_mul_f32 v[74:75], v[4:5], v[2:3] op_sel_hi:[1,0]
	v_add_f32_e32 v72, 1.0, v72
	v_mul_f32_e32 v2, 0xbfb8aa3b, v74
	v_mul_f32_e32 v74, 0xbfb8aa3b, v75
	v_rcp_f32_e32 v75, v72
	v_mul_f32_e32 v72, 0xbfb8aa3b, v73
	v_exp_f32_e32 v2, v2
	v_exp_f32_e32 v74, v74
	v_exp_f32_e32 v72, v72
	v_add_f32_e32 v2, 1.0, v2
	v_add_f32_e32 v74, 1.0, v74
	v_add_f32_e32 v72, 1.0, v72
	v_rcp_f32_e32 v2, v2
	v_rcp_f32_e32 v74, v74
	v_rcp_f32_e32 v80, v72
	v_lshl_add_u64 v[72:73], v[70:71], 0, v[68:69]
	v_add_co_u32_e32 v72, vcc, s2, v72
	v_cvt_pk_bf16_f32 v68, v76, v77
	v_cvt_pk_bf16_f32 v69, v78, v79
	v_cvt_pk_bf16_f32 v70, v2, v74
	v_cvt_pk_bf16_f32 v71, v75, v80
	v_addc_co_u32_e32 v73, vcc, 0, v73, vcc
	global_store_dwordx4 v[72:73], v[68:71], off offset:768

.LBB0_178:
	s_and_b64 vcc, exec, s[4:5]
	s_cbranch_vccz .LBB0_181
	s_lshl_b32 s4, s48, 8
	s_add_i32 s4, s4, s31
	v_or_b32_e32 v70, s4, v181
	v_ashrrev_i32_e32 v71, 31, v70
	v_lshl_add_u64 v[78:79], v[70:71], 2, s[70:71]
	v_mov_b32_e32 v80, v164
	v_mov_b32_e32 v82, v165
	v_mov_b32_e32 v74, v166
	v_mov_b32_e32 v72, v167
	s_or_b32 s5, s16, s49
	v_or_b32_e32 v2, s5, v242
	s_add_i32 s20, s5, 0xfffff180
	s_add_i32 s21, s4, 0xffffc000
	s_movk_i32 s36, 0x4000
	v_bitop3_b32 v76, s5, 56, v242 bitop3:0xc8
	s_ashr_i32 s5, s20, 6
	v_add_u32_e32 v2, 0xfffff184, v2
	s_ashr_i32 s20, s4, 11
	v_bitop3_b32 v71, s4, v250, v181 bitop3:0xc8
	s_lshr_b32 s21, s21, 4
	v_ashrrev_i32_e32 v75, 6, v2
	v_add_u32_e32 v2, 0x80, v71
	v_mov_b32_e32 v71, s20
	v_mov_b32_e32 v81, s21
	v_cmp_gt_i32_e32 vcc, s36, v70
	v_mov_b64_e32 v[68:69], s[92:93]
	v_or_b32_e32 v73, 4, v76
	v_cndmask_b32_e32 v78, v81, v71, vcc
	v_lshlrev_b32_e32 v79, 1, v78
	v_add_u32_e32 v78, s5, v79
	v_add_u32_e32 v84, v79, v75
	v_ashrrev_i32_e32 v79, 31, v78
	v_lshlrev_b64 v[78:79], 6, v[78:79]
	v_or_b32_e32 v78, v78, v76
	v_cndmask_b32_e32 v2, v244, v2, vcc
	v_ashrrev_i32_e32 v85, 31, v84
	v_mad_u64_u32 v[86:87], s[20:21], v78, s89, v[68:69]
	v_lshlrev_b32_e32 v2, 1, v2
	v_lshlrev_b64 v[84:85], 6, v[84:85]
	v_mad_i32_i24 v87, v79, s89, v87
	v_or_b32_e32 v81, v84, v73
	v_lshl_add_u64 v[78:79], v[86:87], 0, v[2:3]
	s_movk_i32 s40, 0x1000
	v_mad_u64_u32 v[88:89], s[20:21], v81, s89, v[68:69]
	v_add_co_u32_e32 v86, vcc, s40, v78
	v_mad_i32_i24 v89, v85, s89, v89
	s_nop 0
	v_addc_co_u32_e32 v87, vcc, 0, v79, vcc
	s_movk_i32 s37, 0x2000
	v_lshl_add_u64 v[84:85], v[88:89], 0, v[2:3]
	v_add_co_u32_e32 v88, vcc, s37, v78
	s_movk_i32 s41, 0x3000
	s_nop 0
	v_addc_co_u32_e32 v89, vcc, 0, v79, vcc
	v_add_co_u32_e32 v90, vcc, s41, v78
	s_movk_i32 s20, 0x7df
	s_nop 0
	v_addc_co_u32_e32 v91, vcc, 0, v79, vcc
	v_add_co_u32_e32 v92, vcc, s40, v84
	v_or_b32_e32 v77, 16, v70
	s_nop 0
	v_addc_co_u32_e32 v93, vcc, 0, v85, vcc
	v_add_co_u32_e32 v94, vcc, s37, v84
	v_or_b32_e32 v102, 32, v70
	s_nop 0
	v_addc_co_u32_e32 v95, vcc, 0, v85, vcc
	v_or_b32_e32 v103, 48, v70
	v_pk_mul_f32 v[98:99], v[64:65], v[80:81] op_sel_hi:[1,0]
	v_pk_mul_f32 v[96:97], v[66:67], v[80:81] op_sel_hi:[1,0]
	v_pk_mul_f32 v[100:101], v[62:63], v[80:81] op_sel_hi:[1,0]
	v_pk_mul_f32 v[80:81], v[60:61], v[80:81] op_sel_hi:[1,0]
	v_cvt_pk_bf16_f32 v2, v98, s0
	v_cvt_pk_bf16_f32 v83, v99, s0
	v_cvt_pk_bf16_f32 v96, v96, s0
	v_cvt_pk_bf16_f32 v97, v97, s0
	v_cvt_pk_bf16_f32 v80, v80, s0
	v_cvt_pk_bf16_f32 v81, v81, s0
	v_cvt_pk_bf16_f32 v98, v100, s0
	global_store_short v[78:79], v2, off
	global_store_short v[86:87], v83, off offset:256
	global_store_short v[88:89], v96, off offset:512
	global_store_short v[90:91], v97, off offset:768
	global_store_short v[84:85], v80, off
	global_store_short v[92:93], v81, off offset:256
	global_store_short v[94:95], v98, off offset:512
	v_add_co_u32_e32 v78, vcc, s41, v84
	v_bitop3_b32 v2, v70, s20, 16 bitop3:0xc8
	s_add_i32 s20, s4, 0xffffc010
	v_cvt_pk_bf16_f32 v99, v101, s0
	v_addc_co_u32_e32 v79, vcc, 0, v85, vcc
	s_lshr_b32 s20, s20, 4
	global_store_short v[78:79], v99, off offset:768
	v_pk_mul_f32 v[78:79], v[58:59], v[82:83] op_sel_hi:[1,0]
	v_pk_mul_f32 v[80:81], v[56:57], v[82:83] op_sel_hi:[1,0]
	v_mov_b32_e32 v83, s20
	v_cmp_gt_i32_e32 vcc, s36, v77
	v_add_u32_e32 v2, 0x80, v2
	v_cvt_pk_bf16_f32 v80, v80, s0
	v_cndmask_b32_e32 v77, v83, v71, vcc
	v_lshlrev_b32_e32 v77, 1, v77
	v_add_u32_e32 v84, s5, v77
	v_ashrrev_i32_e32 v85, 31, v84
	v_lshlrev_b64 v[84:85], 6, v[84:85]
	v_or_b32_e32 v83, v84, v76
	v_cndmask_b32_e32 v2, v244, v2, vcc
	v_mad_u64_u32 v[86:87], s[20:21], v83, s89, v[68:69]
	v_mad_i32_i24 v87, v85, s89, v87
	v_lshlrev_b32_e32 v2, 1, v2
	v_lshl_add_u64 v[84:85], v[86:87], 0, v[2:3]
	global_store_short v[84:85], v80, off
	v_add_co_u32_e32 v80, vcc, s40, v84
	v_cvt_pk_bf16_f32 v83, v81, s0
	s_nop 0
	v_addc_co_u32_e32 v81, vcc, 0, v85, vcc
	global_store_short v[80:81], v83, off offset:256
	v_add_co_u32_e32 v80, vcc, s37, v84
	v_cvt_pk_bf16_f32 v78, v78, s0
	s_nop 0
	v_addc_co_u32_e32 v81, vcc, 0, v85, vcc
	global_store_short v[80:81], v78, off offset:512
	v_add_co_u32_e32 v78, vcc, s41, v84
	v_cvt_pk_bf16_f32 v80, v79, s0
	s_nop 0
	v_addc_co_u32_e32 v79, vcc, 0, v85, vcc
	global_store_short v[78:79], v80, off offset:768
	v_pk_mul_f32 v[78:79], v[54:55], v[82:83] op_sel_hi:[1,0]
	v_pk_mul_f32 v[80:81], v[52:53], v[82:83] op_sel_hi:[1,0]
	v_add_u32_e32 v82, v77, v75
	v_ashrrev_i32_e32 v83, 31, v82
	v_lshlrev_b64 v[82:83], 6, v[82:83]
	v_or_b32_e32 v77, v82, v73
	v_mad_u64_u32 v[84:85], s[20:21], v77, s89, v[68:69]
	v_mad_i32_i24 v85, v83, s89, v85
	v_lshl_add_u64 v[82:83], v[84:85], 0, v[2:3]
	v_cvt_pk_bf16_f32 v2, v80, s0
	v_add_co_u32_e32 v80, vcc, s40, v82
	global_store_short v[82:83], v2, off
	v_cvt_pk_bf16_f32 v2, v81, s0
	v_addc_co_u32_e32 v81, vcc, 0, v83, vcc
	global_store_short v[80:81], v2, off offset:256
	v_add_co_u32_e32 v80, vcc, s37, v82
	v_cvt_pk_bf16_f32 v2, v78, s0
	s_nop 0
	v_addc_co_u32_e32 v81, vcc, 0, v83, vcc
	v_add_co_u32_e32 v78, vcc, s41, v82
	global_store_short v[80:81], v2, off offset:512
	v_cvt_pk_bf16_f32 v2, v79, s0
	v_addc_co_u32_e32 v79, vcc, 0, v83, vcc
	s_movk_i32 s20, 0x7ef
	global_store_short v[78:79], v2, off offset:768
	v_bitop3_b32 v2, v70, s20, 32 bitop3:0xc8
	s_add_i32 s20, s4, 0xffffc020
	s_lshr_b32 s20, s20, 4
	v_mov_b32_e32 v77, s20
	v_cmp_gt_i32_e32 vcc, s36, v102
	v_add_u32_e32 v2, 0x80, v2
	v_pk_mul_f32 v[80:81], v[48:49], v[74:75] op_sel_hi:[1,0]
	v_cndmask_b32_e32 v77, v77, v71, vcc
	v_lshlrev_b32_e32 v77, 1, v77
	v_add_u32_e32 v82, s5, v77
	v_ashrrev_i32_e32 v83, 31, v82
	v_lshlrev_b64 v[82:83], 6, v[82:83]
	v_or_b32_e32 v82, v82, v76
	v_cndmask_b32_e32 v2, v244, v2, vcc
	v_mad_u64_u32 v[84:85], s[20:21], v82, s89, v[68:69]
	v_mad_i32_i24 v85, v83, s89, v85
	v_lshlrev_b32_e32 v2, 1, v2
	v_lshl_add_u64 v[82:83], v[84:85], 0, v[2:3]
	v_cvt_pk_bf16_f32 v80, v80, s0
	global_store_short v[82:83], v80, off
	v_add_co_u32_e32 v80, vcc, s40, v82
	v_cvt_pk_bf16_f32 v84, v81, s0
	s_nop 0
	v_addc_co_u32_e32 v81, vcc, 0, v83, vcc
	v_pk_mul_f32 v[78:79], v[50:51], v[74:75] op_sel_hi:[1,0]
	global_store_short v[80:81], v84, off offset:256
	v_add_co_u32_e32 v80, vcc, s37, v82
	v_cvt_pk_bf16_f32 v78, v78, s0
	s_nop 0
	v_addc_co_u32_e32 v81, vcc, 0, v83, vcc
	global_store_short v[80:81], v78, off offset:512
	v_add_co_u32_e32 v78, vcc, s41, v82
	v_add_u32_e32 v82, v77, v75
	v_cvt_pk_bf16_f32 v80, v79, s0
	v_addc_co_u32_e32 v79, vcc, 0, v83, vcc
	v_ashrrev_i32_e32 v83, 31, v82
	v_lshlrev_b64 v[82:83], 6, v[82:83]
	global_store_short v[78:79], v80, off offset:768
	v_pk_mul_f32 v[78:79], v[46:47], v[74:75] op_sel_hi:[1,0]
	v_pk_mul_f32 v[80:81], v[44:45], v[74:75] op_sel_hi:[1,0]
	v_or_b32_e32 v74, v82, v73
	v_mad_u64_u32 v[84:85], s[20:21], v74, s89, v[68:69]
	v_mad_i32_i24 v85, v83, s89, v85
	v_lshl_add_u64 v[82:83], v[84:85], 0, v[2:3]
	v_cvt_pk_bf16_f32 v2, v80, s0
	v_add_co_u32_e32 v80, vcc, s40, v82
	global_store_short v[82:83], v2, off
	v_cvt_pk_bf16_f32 v2, v81, s0
	v_addc_co_u32_e32 v81, vcc, 0, v83, vcc
	global_store_short v[80:81], v2, off offset:256
	v_add_co_u32_e32 v80, vcc, s37, v82
	v_cvt_pk_bf16_f32 v2, v78, s0
	s_nop 0
	v_addc_co_u32_e32 v81, vcc, 0, v83, vcc
	v_add_co_u32_e32 v78, vcc, s41, v82
	global_store_short v[80:81], v2, off offset:512
	v_cvt_pk_bf16_f32 v2, v79, s0
	v_addc_co_u32_e32 v79, vcc, 0, v83, vcc
	s_movk_i32 s20, 0x7ff
	global_store_short v[78:79], v2, off offset:768
	v_bitop3_b32 v2, v70, s20, 48 bitop3:0xc8
	s_add_i32 s20, s4, 0xffffc030
	s_lshr_b32 s20, s20, 4
	v_mov_b32_e32 v70, s20
	v_cmp_gt_i32_e32 vcc, s36, v103
	v_add_u32_e32 v2, 0x80, v2
	v_pk_mul_f32 v[80:81], v[40:41], v[72:73] op_sel_hi:[1,0]
	v_cndmask_b32_e32 v70, v70, v71, vcc
	v_lshlrev_b32_e32 v74, 1, v70
	v_add_u32_e32 v70, s5, v74
	v_ashrrev_i32_e32 v71, 31, v70
	v_lshlrev_b64 v[70:71], 6, v[70:71]
	v_or_b32_e32 v70, v70, v76
	v_cndmask_b32_e32 v2, v244, v2, vcc
	v_mad_u64_u32 v[82:83], s[20:21], v70, s89, v[68:69]
	v_mad_i32_i24 v83, v71, s89, v83
	v_lshlrev_b32_e32 v2, 1, v2
	v_lshl_add_u64 v[70:71], v[82:83], 0, v[2:3]
	v_cvt_pk_bf16_f32 v77, v80, s0
	v_add_co_u32_e32 v80, vcc, s40, v70
	global_store_short v[70:71], v77, off
	v_cvt_pk_bf16_f32 v77, v81, s0
	v_addc_co_u32_e32 v81, vcc, 0, v71, vcc
	v_pk_mul_f32 v[78:79], v[42:43], v[72:73] op_sel_hi:[1,0]
	global_store_short v[80:81], v77, off offset:256
	v_add_co_u32_e32 v80, vcc, s37, v70
	v_cvt_pk_bf16_f32 v77, v78, s0
	s_nop 0
	v_addc_co_u32_e32 v81, vcc, 0, v71, vcc
	global_store_short v[80:81], v77, off offset:512
	v_add_u32_e32 v80, v74, v75
	v_add_co_u32_e32 v70, vcc, s41, v70
	v_ashrrev_i32_e32 v81, 31, v80
	v_cvt_pk_bf16_f32 v77, v79, s0
	v_addc_co_u32_e32 v71, vcc, 0, v71, vcc
	v_lshlrev_b64 v[80:81], 6, v[80:81]
	global_store_short v[70:71], v77, off offset:768
	v_pk_mul_f32 v[70:71], v[38:39], v[72:73] op_sel_hi:[1,0]
	v_pk_mul_f32 v[78:79], v[36:37], v[72:73] op_sel_hi:[1,0]
	v_or_b32_e32 v72, v80, v73
	v_mad_u64_u32 v[68:69], s[20:21], v72, s89, v[68:69]
	v_mad_i32_i24 v69, v81, s89, v69
	v_lshl_add_u64 v[68:69], v[68:69], 0, v[2:3]
	v_cvt_pk_bf16_f32 v2, v78, s0
	v_add_co_u32_e32 v78, vcc, 0x1000, v68
	global_store_short v[68:69], v2, off
	v_cvt_pk_bf16_f32 v2, v79, s0
	v_addc_co_u32_e32 v79, vcc, 0, v69, vcc
	global_store_short v[78:79], v2, off offset:256
	v_add_co_u32_e32 v78, vcc, 0x2000, v68
	v_cvt_pk_bf16_f32 v2, v70, s0
	s_nop 0
	v_addc_co_u32_e32 v79, vcc, 0, v69, vcc
	v_add_co_u32_e32 v68, vcc, 0x3000, v68
	s_movk_i32 s20, 0x4000
	global_store_short v[78:79], v2, off offset:512
	v_cvt_pk_bf16_f32 v2, v71, s0
	v_addc_co_u32_e32 v69, vcc, 0, v69, vcc
	s_cmp_eq_u32 s48, 64
	global_store_short v[68:69], v2, off offset:768
	s_cbranch_scc1 .LBB0_181
	s_add_i32 s20, s4, 0x80
	v_or_b32_e32 v70, s20, v181
	v_ashrrev_i32_e32 v71, 31, v70
	v_lshl_add_u64 v[78:79], v[70:71], 2, s[70:71]
	v_mov_b32_e32 v74, v246
	v_mov_b32_e32 v80, v247
	s_add_i32 s21, s4, 0xffffc080
	s_movk_i32 s37, 0x4000
	s_ashr_i32 s36, s20, 11
	v_bitop3_b32 v2, s20, v250, v181 bitop3:0xc8
	s_lshr_b32 s20, s21, 4
	v_mov_b32_e32 v72, s20
	v_mov_b32_e32 v111, s36
	v_cmp_gt_i32_e32 vcc, s37, v70
	v_mov_b64_e32 v[68:69], s[92:93]
	v_add_u32_e32 v2, 0x80, v2
	v_cndmask_b32_e32 v83, v72, v111, vcc
	v_mov_b32_e32 v82, v248
	v_mov_b32_e32 v72, v249
	v_lshlrev_b32_e32 v79, 1, v83
	v_add_u32_e32 v78, s5, v79
	v_add_u32_e32 v84, v79, v75
	v_ashrrev_i32_e32 v79, 31, v78
	v_lshlrev_b64 v[78:79], 6, v[78:79]
	s_movk_i32 s20, 0x7df
	v_or_b32_e32 v78, v78, v76
	v_bitop3_b32 v81, v70, s20, 16 bitop3:0xc8
	v_cndmask_b32_e32 v2, v244, v2, vcc
	v_ashrrev_i32_e32 v85, 31, v84
	v_mad_u64_u32 v[86:87], s[20:21], v78, s89, v[68:69]
	v_lshlrev_b32_e32 v2, 1, v2
	v_lshlrev_b64 v[84:85], 6, v[84:85]
	v_mad_i32_i24 v87, v79, s89, v87
	v_or_b32_e32 v83, v84, v73
	v_lshl_add_u64 v[78:79], v[86:87], 0, v[2:3]
	v_mad_u64_u32 v[88:89], s[20:21], v83, s89, v[68:69]
	v_add_co_u32_e32 v86, vcc, s40, v78
	v_mad_i32_i24 v89, v85, s89, v89
	s_nop 0
	v_addc_co_u32_e32 v87, vcc, 0, v79, vcc
	s_movk_i32 s36, 0x2000
	v_lshl_add_u64 v[84:85], v[88:89], 0, v[2:3]
	v_add_co_u32_e32 v88, vcc, s36, v78
	s_add_i32 s20, s4, 0xffffc090
	s_nop 0
	v_addc_co_u32_e32 v89, vcc, 0, v79, vcc
	v_add_co_u32_e32 v90, vcc, s41, v78
	v_or_b32_e32 v71, 16, v70
	s_nop 0
	v_addc_co_u32_e32 v91, vcc, 0, v79, vcc
	v_add_co_u32_e32 v92, vcc, s40, v84
	s_lshr_b32 s20, s20, 4
	s_nop 0
	v_addc_co_u32_e32 v93, vcc, 0, v85, vcc
	v_add_co_u32_e32 v94, vcc, s36, v84
	v_or_b32_e32 v77, 32, v70
	s_nop 0
	v_addc_co_u32_e32 v95, vcc, 0, v85, vcc
	v_add_co_u32_e32 v96, vcc, s41, v84
	v_or_b32_e32 v110, 48, v70
	s_nop 0
	v_addc_co_u32_e32 v97, vcc, 0, v85, vcc
	v_cmp_gt_i32_e32 vcc, s37, v71
	v_pk_mul_f32 v[100:101], v[32:33], v[74:75] op_sel_hi:[1,0]
	v_pk_mul_f32 v[98:99], v[34:35], v[74:75] op_sel_hi:[1,0]
	v_pk_mul_f32 v[102:103], v[30:31], v[74:75] op_sel_hi:[1,0]
	v_pk_mul_f32 v[104:105], v[28:29], v[74:75] op_sel_hi:[1,0]
	v_cvt_pk_bf16_f32 v2, v100, s0
	v_cvt_pk_bf16_f32 v74, v101, s0
	v_cvt_pk_bf16_f32 v83, v98, s0
	v_cvt_pk_bf16_f32 v98, v99, s0
	v_cvt_pk_bf16_f32 v99, v104, s0
	v_cvt_pk_bf16_f32 v100, v105, s0
	v_cvt_pk_bf16_f32 v101, v102, s0
	v_cvt_pk_bf16_f32 v102, v103, s0
	global_store_short v[78:79], v2, off
	global_store_short v[86:87], v74, off offset:256
	global_store_short v[88:89], v83, off offset:512
	global_store_short v[90:91], v98, off offset:768
	global_store_short v[84:85], v99, off
	global_store_short v[92:93], v100, off offset:256
	global_store_short v[94:95], v101, off offset:512
	global_store_short v[96:97], v102, off offset:768
	v_mov_b32_e32 v74, s20
	v_cndmask_b32_e32 v71, v74, v111, vcc
	v_lshlrev_b32_e32 v71, 1, v71
	v_add_u32_e32 v78, s5, v71
	v_ashrrev_i32_e32 v79, 31, v78
	v_lshlrev_b64 v[78:79], 6, v[78:79]
	v_add_u32_e32 v2, 0x80, v81
	v_or_b32_e32 v74, v78, v76
	v_cndmask_b32_e32 v2, v244, v2, vcc
	v_mad_u64_u32 v[84:85], s[20:21], v74, s89, v[68:69]
	v_mad_i32_i24 v85, v79, s89, v85
	v_lshlrev_b32_e32 v2, 1, v2
	v_pk_mul_f32 v[108:109], v[24:25], v[80:81] op_sel_hi:[1,0]
	v_lshl_add_u64 v[78:79], v[84:85], 0, v[2:3]
	v_cvt_pk_bf16_f32 v74, v108, s0
	v_add_co_u32_e32 v84, vcc, s40, v78
	global_store_short v[78:79], v74, off
	v_cvt_pk_bf16_f32 v74, v109, s0
	v_addc_co_u32_e32 v85, vcc, 0, v79, vcc
	v_pk_mul_f32 v[106:107], v[26:27], v[80:81] op_sel_hi:[1,0]
	global_store_short v[84:85], v74, off offset:256
	v_add_co_u32_e32 v84, vcc, s36, v78
	v_cvt_pk_bf16_f32 v74, v106, s0
	s_nop 0
	v_addc_co_u32_e32 v85, vcc, 0, v79, vcc
	global_store_short v[84:85], v74, off offset:512
	v_add_u32_e32 v84, v71, v75
	v_ashrrev_i32_e32 v85, 31, v84
	v_lshlrev_b64 v[84:85], 6, v[84:85]
	v_or_b32_e32 v71, v84, v73
	v_add_co_u32_e32 v78, vcc, s41, v78
	v_mad_u64_u32 v[86:87], s[20:21], v71, s89, v[68:69]
	v_cvt_pk_bf16_f32 v74, v107, s0
	v_addc_co_u32_e32 v79, vcc, 0, v79, vcc
	v_mad_i32_i24 v87, v85, s89, v87
	global_store_short v[78:79], v74, off offset:768
	v_pk_mul_f32 v[78:79], v[22:23], v[80:81] op_sel_hi:[1,0]
	v_pk_mul_f32 v[80:81], v[20:21], v[80:81] op_sel_hi:[1,0]
	v_lshl_add_u64 v[84:85], v[86:87], 0, v[2:3]
	v_cvt_pk_bf16_f32 v2, v80, s0
	v_add_co_u32_e32 v80, vcc, s40, v84
	global_store_short v[84:85], v2, off
	v_cvt_pk_bf16_f32 v2, v81, s0
	v_addc_co_u32_e32 v81, vcc, 0, v85, vcc
	global_store_short v[80:81], v2, off offset:256
	v_add_co_u32_e32 v80, vcc, s36, v84
	v_cvt_pk_bf16_f32 v2, v78, s0
	s_nop 0
	v_addc_co_u32_e32 v81, vcc, 0, v85, vcc
	v_add_co_u32_e32 v78, vcc, s41, v84
	global_store_short v[80:81], v2, off offset:512
	v_cvt_pk_bf16_f32 v2, v79, s0
	v_addc_co_u32_e32 v79, vcc, 0, v85, vcc
	s_movk_i32 s20, 0x7ef
	global_store_short v[78:79], v2, off offset:768
	v_bitop3_b32 v2, v70, s20, 32 bitop3:0xc8
	s_add_i32 s20, s4, 0xffffc0a0
	s_lshr_b32 s20, s20, 4
	v_mov_b32_e32 v71, s20
	v_cmp_gt_i32_e32 vcc, s37, v77
	v_add_u32_e32 v2, 0x80, v2
	v_pk_mul_f32 v[80:81], v[16:17], v[82:83] op_sel_hi:[1,0]
	v_cndmask_b32_e32 v71, v71, v111, vcc
	v_lshlrev_b32_e32 v71, 1, v71
	v_add_u32_e32 v84, s5, v71
	v_ashrrev_i32_e32 v85, 31, v84
	v_lshlrev_b64 v[84:85], 6, v[84:85]
	v_or_b32_e32 v74, v84, v76
	v_cndmask_b32_e32 v2, v244, v2, vcc
	v_mad_u64_u32 v[86:87], s[20:21], v74, s89, v[68:69]
	v_mad_i32_i24 v87, v85, s89, v87
	v_lshlrev_b32_e32 v2, 1, v2
	v_lshl_add_u64 v[84:85], v[86:87], 0, v[2:3]
	v_cvt_pk_bf16_f32 v74, v80, s0
	v_add_co_u32_e32 v80, vcc, s40, v84
	global_store_short v[84:85], v74, off
	v_cvt_pk_bf16_f32 v74, v81, s0
	v_addc_co_u32_e32 v81, vcc, 0, v85, vcc
	global_store_short v[80:81], v74, off offset:256
	v_add_co_u32_e32 v80, vcc, s36, v84
	v_pk_mul_f32 v[78:79], v[18:19], v[82:83] op_sel_hi:[1,0]
	s_nop 0
	v_addc_co_u32_e32 v81, vcc, 0, v85, vcc
	v_cvt_pk_bf16_f32 v74, v78, s0
	v_add_co_u32_e32 v78, vcc, s41, v84
	global_store_short v[80:81], v74, off offset:512
	v_cvt_pk_bf16_f32 v74, v79, s0
	v_addc_co_u32_e32 v79, vcc, 0, v85, vcc
	global_store_short v[78:79], v74, off offset:768
	v_pk_mul_f32 v[78:79], v[14:15], v[82:83] op_sel_hi:[1,0]
	v_pk_mul_f32 v[80:81], v[12:13], v[82:83] op_sel_hi:[1,0]
	v_add_u32_e32 v82, v71, v75
	v_ashrrev_i32_e32 v83, 31, v82
	v_lshlrev_b64 v[82:83], 6, v[82:83]
	v_or_b32_e32 v71, v82, v73
	v_mad_u64_u32 v[84:85], s[20:21], v71, s89, v[68:69]
	v_mad_i32_i24 v85, v83, s89, v85
	v_lshl_add_u64 v[82:83], v[84:85], 0, v[2:3]
	v_cvt_pk_bf16_f32 v2, v80, s0
	v_add_co_u32_e32 v80, vcc, s40, v82
	global_store_short v[82:83], v2, off
	v_cvt_pk_bf16_f32 v2, v81, s0
	v_addc_co_u32_e32 v81, vcc, 0, v83, vcc
	global_store_short v[80:81], v2, off offset:256
	v_add_co_u32_e32 v80, vcc, s36, v82
	v_cvt_pk_bf16_f32 v2, v78, s0
	s_nop 0
	v_addc_co_u32_e32 v81, vcc, 0, v83, vcc
	v_add_co_u32_e32 v78, vcc, s41, v82
	s_addk_i32 s4, 0xc0b0
	s_movk_i32 s20, 0x4000
	global_store_short v[80:81], v2, off offset:512
	v_cvt_pk_bf16_f32 v2, v79, s0
	v_addc_co_u32_e32 v79, vcc, 0, v83, vcc
	s_movk_i32 s21, 0x7ff
	s_lshr_b32 s4, s4, 4
	global_store_short v[78:79], v2, off offset:768
	v_bitop3_b32 v2, v70, s21, 48 bitop3:0xc8
	v_mov_b32_e32 v70, s4
	v_cmp_gt_i32_e32 vcc, s20, v110
	v_add_u32_e32 v2, 0x80, v2
	v_pk_mul_f32 v[80:81], v[8:9], v[72:73] op_sel_hi:[1,0]
	v_cndmask_b32_e32 v70, v70, v111, vcc
	v_lshlrev_b32_e32 v74, 1, v70
	v_add_u32_e32 v70, s5, v74
	v_ashrrev_i32_e32 v71, 31, v70
	v_lshlrev_b64 v[70:71], 6, v[70:71]
	v_or_b32_e32 v70, v70, v76
	v_cndmask_b32_e32 v2, v244, v2, vcc
	v_mad_u64_u32 v[76:77], s[4:5], v70, s89, v[68:69]
	v_mad_i32_i24 v77, v71, s89, v77
	v_lshlrev_b32_e32 v2, 1, v2
	v_lshl_add_u64 v[70:71], v[76:77], 0, v[2:3]
	v_cvt_pk_bf16_f32 v76, v80, s0
	global_store_short v[70:71], v76, off
	v_add_co_u32_e32 v76, vcc, s40, v70
	v_cvt_pk_bf16_f32 v80, v81, s0
	s_nop 0
	v_addc_co_u32_e32 v77, vcc, 0, v71, vcc
	global_store_short v[76:77], v80, off offset:256
	v_add_co_u32_e32 v76, vcc, s36, v70
	v_pk_mul_f32 v[78:79], v[10:11], v[72:73] op_sel_hi:[1,0]
	s_nop 0
	v_addc_co_u32_e32 v77, vcc, 0, v71, vcc
	v_add_u32_e32 v74, v74, v75
	v_cvt_pk_bf16_f32 v78, v78, s0
	v_add_co_u32_e32 v70, vcc, s41, v70
	v_ashrrev_i32_e32 v75, 31, v74
	global_store_short v[76:77], v78, off offset:512
	v_cvt_pk_bf16_f32 v76, v79, s0
	v_addc_co_u32_e32 v71, vcc, 0, v71, vcc
	v_lshlrev_b64 v[74:75], 6, v[74:75]
	global_store_short v[70:71], v76, off offset:768
	v_pk_mul_f32 v[70:71], v[6:7], v[72:73] op_sel_hi:[1,0]
	v_pk_mul_f32 v[76:77], v[4:5], v[72:73] op_sel_hi:[1,0]
	v_or_b32_e32 v72, v74, v73
	v_mad_u64_u32 v[68:69], s[4:5], v72, s89, v[68:69]
	v_mad_i32_i24 v69, v75, s89, v69
	v_lshl_add_u64 v[68:69], v[68:69], 0, v[2:3]
	v_cvt_pk_bf16_f32 v2, v76, s0
	v_add_co_u32_e32 v72, vcc, 0x1000, v68
	global_store_short v[68:69], v2, off
	v_cvt_pk_bf16_f32 v2, v77, s0
	v_addc_co_u32_e32 v73, vcc, 0, v69, vcc
	global_store_short v[72:73], v2, off offset:256
	v_add_co_u32_e32 v72, vcc, 0x2000, v68
	v_cvt_pk_bf16_f32 v2, v70, s0
	s_nop 0
	v_addc_co_u32_e32 v73, vcc, 0, v69, vcc
	v_add_co_u32_e32 v68, vcc, 0x3000, v68
	global_store_short v[72:73], v2, off offset:512
	v_cvt_pk_bf16_f32 v2, v71, s0
	v_addc_co_u32_e32 v69, vcc, 0, v69, vcc
	global_store_short v[68:69], v2, off offset:768

.LBB0_225:
	s_and_b64 vcc, exec, s[0:1]
	s_cbranch_vccz .LBB0_228
	s_lshl_b32 s0, s48, 8
	v_add_u32_e32 v70, s0, v241
	v_ashrrev_i32_e32 v71, 31, v70
	v_lshl_add_u64 v[68:69], v[70:71], 2, s[70:71]
	v_mov_b32_e32 v86, v164
	v_mov_b32_e32 v80, v165
	v_mov_b32_e32 v76, v166
	v_mov_b32_e32 v2, v167
	s_ashr_i32 s75, s74, 31
	s_mov_b32 s0, 0x643f000
	v_or_b32_e32 v78, 16, v70
	v_ashrrev_i32_e32 v79, 31, v78
	v_lshlrev_b64 v[78:79], 11, v[78:79]
	v_lshl_add_u64 v[78:79], s[94:95], 0, v[78:79]
	v_or_b32_e32 v74, 32, v70
	v_ashrrev_i32_e32 v75, 31, v74
	v_lshlrev_b64 v[74:75], 11, v[74:75]
	v_lshl_add_u64 v[74:75], s[94:95], 0, v[74:75]
	v_or_b32_e32 v72, 48, v70
	v_ashrrev_i32_e32 v73, 31, v72
	v_lshlrev_b64 v[72:73], 11, v[72:73]
	v_lshl_add_u64 v[72:73], s[94:95], 0, v[72:73]
	s_cmp_eq_u32 s48, 64
	v_pk_mul_f32 v[82:83], v[64:65], v[86:87] op_sel_hi:[1,0]
	s_nop 0
	v_mul_f32_e32 v77, 0xbfb8aa3b, v82
	v_exp_f32_e32 v77, v77
	v_pk_mul_f32 v[68:69], v[66:67], v[86:87] op_sel_hi:[1,0]
	v_add_f32_e32 v77, 1.0, v77
	v_rcp_f32_e32 v84, v77
	v_mul_f32_e32 v77, 0xbfb8aa3b, v83
	v_exp_f32_e32 v77, v77
	s_nop 0
	v_add_f32_e32 v77, 1.0, v77
	v_rcp_f32_e32 v85, v77
	v_mul_f32_e32 v77, 0xbfb8aa3b, v68
	v_exp_f32_e32 v77, v77
	v_pk_mul_f32 v[82:83], v[82:83], v[84:85]
	s_nop 0
	v_cvt_pk_bf16_f32 v82, v82, v83
	v_add_f32_e32 v77, 1.0, v77
	v_rcp_f32_e32 v84, v77
	v_mul_f32_e32 v77, 0xbfb8aa3b, v69
	v_exp_f32_e32 v77, v77
	s_nop 0
	v_add_f32_e32 v77, 1.0, v77
	v_rcp_f32_e32 v85, v77
	s_nop 0
	v_pk_mul_f32 v[84:85], v[68:69], v[84:85]
	v_pk_mul_f32 v[68:69], v[62:63], v[86:87] op_sel_hi:[1,0]
	v_pk_mul_f32 v[86:87], v[60:61], v[86:87] op_sel_hi:[1,0]
	v_cvt_pk_bf16_f32 v83, v84, v85
	v_mul_f32_e32 v77, 0xbfb8aa3b, v86
	v_exp_f32_e32 v77, v77
	s_nop 0
	v_add_f32_e32 v77, 1.0, v77
	v_rcp_f32_e32 v88, v77
	v_mul_f32_e32 v77, 0xbfb8aa3b, v87
	v_exp_f32_e32 v77, v77
	s_nop 0
	v_add_f32_e32 v77, 1.0, v77
	v_rcp_f32_e32 v89, v77
	v_mul_f32_e32 v77, 0xbfb8aa3b, v68
	v_exp_f32_e32 v77, v77
	v_pk_mul_f32 v[86:87], v[86:87], v[88:89]
	s_nop 0
	v_cvt_pk_bf16_f32 v84, v86, v87
	v_add_f32_e32 v77, 1.0, v77
	v_rcp_f32_e32 v88, v77
	v_mul_f32_e32 v77, 0xbfb8aa3b, v69
	v_exp_f32_e32 v77, v77
	s_nop 0
	v_add_f32_e32 v77, 1.0, v77
	v_rcp_f32_e32 v89, v77
	s_nop 0
	v_pk_mul_f32 v[88:89], v[68:69], v[88:89]
	v_lshlrev_b64 v[68:69], 11, v[70:71]
	v_lshl_add_u64 v[90:91], s[94:95], 0, v[68:69]
	v_lshl_add_u64 v[68:69], s[74:75], 0, v[178:179]
	v_lshlrev_b64 v[68:69], 1, v[68:69]
	v_lshl_add_u64 v[90:91], v[90:91], 0, v[68:69]
	v_add_co_u32_e32 v86, vcc, s0, v90
	v_cvt_pk_bf16_f32 v85, v88, v89
	s_nop 0
	v_addc_co_u32_e32 v87, vcc, 0, v91, vcc
	global_store_dwordx4 v[86:87], v[82:85], off offset:256
	s_nop 1
	v_pk_mul_f32 v[82:83], v[56:57], v[80:81] op_sel_hi:[1,0]
	v_pk_mul_f32 v[84:85], v[58:59], v[80:81] op_sel_hi:[1,0]
	v_mul_f32_e32 v71, 0xbfb8aa3b, v82
	v_exp_f32_e32 v71, v71
	s_nop 0
	v_add_f32_e32 v71, 1.0, v71
	v_rcp_f32_e32 v86, v71
	v_mul_f32_e32 v71, 0xbfb8aa3b, v83
	v_exp_f32_e32 v71, v71
	s_nop 0
	v_add_f32_e32 v71, 1.0, v71
	v_rcp_f32_e32 v87, v71
	v_mul_f32_e32 v71, 0xbfb8aa3b, v84
	v_exp_f32_e32 v71, v71
	v_pk_mul_f32 v[82:83], v[82:83], v[86:87]
	v_add_f32_e32 v71, 1.0, v71
	v_rcp_f32_e32 v86, v71
	v_mul_f32_e32 v71, 0xbfb8aa3b, v85
	v_exp_f32_e32 v71, v71
	s_nop 0
	v_add_f32_e32 v71, 1.0, v71
	v_rcp_f32_e32 v87, v71
	s_nop 0
	v_pk_mul_f32 v[84:85], v[84:85], v[86:87]
	v_pk_mul_f32 v[86:87], v[54:55], v[80:81] op_sel_hi:[1,0]
	v_pk_mul_f32 v[80:81], v[52:53], v[80:81] op_sel_hi:[1,0]
	s_nop 0
	v_mul_f32_e32 v71, 0xbfb8aa3b, v80
	v_exp_f32_e32 v71, v71
	s_nop 0
	v_add_f32_e32 v71, 1.0, v71
	v_rcp_f32_e32 v88, v71
	v_mul_f32_e32 v71, 0xbfb8aa3b, v81
	v_exp_f32_e32 v71, v71
	s_nop 0
	v_add_f32_e32 v71, 1.0, v71
	v_rcp_f32_e32 v89, v71
	v_mul_f32_e32 v71, 0xbfb8aa3b, v86
	v_exp_f32_e32 v71, v71
	v_pk_mul_f32 v[80:81], v[80:81], v[88:89]
	s_nop 0
	v_cvt_pk_bf16_f32 v80, v80, v81
	v_add_f32_e32 v71, 1.0, v71
	v_rcp_f32_e32 v88, v71
	v_mul_f32_e32 v71, 0xbfb8aa3b, v87
	v_exp_f32_e32 v71, v71
	s_nop 0
	v_add_f32_e32 v71, 1.0, v71
	v_rcp_f32_e32 v89, v71
	s_nop 0
	v_pk_mul_f32 v[86:87], v[86:87], v[88:89]
	v_lshl_add_u64 v[88:89], v[78:79], 0, v[68:69]
	v_cvt_pk_bf16_f32 v78, v82, v83
	v_add_co_u32_e32 v82, vcc, s0, v88
	v_cvt_pk_bf16_f32 v79, v84, v85
	v_cvt_pk_bf16_f32 v81, v86, v87
	v_addc_co_u32_e32 v83, vcc, 0, v89, vcc
	global_store_dwordx4 v[82:83], v[78:81], off offset:256
	s_nop 1
	v_pk_mul_f32 v[80:81], v[48:49], v[76:77] op_sel_hi:[1,0]
	v_pk_mul_f32 v[78:79], v[50:51], v[76:77] op_sel_hi:[1,0]
	v_mul_f32_e32 v71, 0xbfb8aa3b, v80
	v_exp_f32_e32 v71, v71
	s_nop 0
	v_add_f32_e32 v71, 1.0, v71
	v_rcp_f32_e32 v82, v71
	v_mul_f32_e32 v71, 0xbfb8aa3b, v81
	v_exp_f32_e32 v71, v71
	s_nop 0
	v_add_f32_e32 v71, 1.0, v71
	v_rcp_f32_e32 v83, v71
	v_mul_f32_e32 v71, 0xbfb8aa3b, v78
	v_exp_f32_e32 v71, v71
	v_pk_mul_f32 v[80:81], v[80:81], v[82:83]
	v_add_f32_e32 v71, 1.0, v71
	v_rcp_f32_e32 v82, v71
	v_mul_f32_e32 v71, 0xbfb8aa3b, v79
	v_exp_f32_e32 v71, v71
	s_nop 0
	v_add_f32_e32 v71, 1.0, v71
	v_rcp_f32_e32 v83, v71
	s_nop 0
	v_pk_mul_f32 v[78:79], v[78:79], v[82:83]
	v_pk_mul_f32 v[82:83], v[46:47], v[76:77] op_sel_hi:[1,0]
	v_pk_mul_f32 v[76:77], v[44:45], v[76:77] op_sel_hi:[1,0]
	s_nop 0
	v_mul_f32_e32 v71, 0xbfb8aa3b, v76
	v_exp_f32_e32 v71, v71
	s_nop 0
	v_add_f32_e32 v71, 1.0, v71
	v_rcp_f32_e32 v84, v71
	v_mul_f32_e32 v71, 0xbfb8aa3b, v77
	v_exp_f32_e32 v71, v71
	s_nop 0
	v_add_f32_e32 v71, 1.0, v71
	v_rcp_f32_e32 v85, v71
	v_mul_f32_e32 v71, 0xbfb8aa3b, v82
	v_exp_f32_e32 v71, v71
	v_pk_mul_f32 v[76:77], v[76:77], v[84:85]
	s_nop 0
	v_cvt_pk_bf16_f32 v76, v76, v77
	v_add_f32_e32 v71, 1.0, v71
	v_rcp_f32_e32 v84, v71
	v_mul_f32_e32 v71, 0xbfb8aa3b, v83
	v_exp_f32_e32 v71, v71
	s_nop 0
	v_add_f32_e32 v71, 1.0, v71
	v_rcp_f32_e32 v85, v71
	s_nop 0
	v_pk_mul_f32 v[82:83], v[82:83], v[84:85]
	v_lshl_add_u64 v[84:85], v[74:75], 0, v[68:69]
	v_cvt_pk_bf16_f32 v75, v78, v79
	v_add_co_u32_e32 v78, vcc, s0, v84
	v_cvt_pk_bf16_f32 v74, v80, v81
	v_cvt_pk_bf16_f32 v77, v82, v83
	v_addc_co_u32_e32 v79, vcc, 0, v85, vcc
	global_store_dwordx4 v[78:79], v[74:77], off offset:256
	v_pk_mul_f32 v[80:81], v[36:37], v[2:3] op_sel_hi:[1,0]
	s_nop 0
	v_pk_mul_f32 v[76:77], v[40:41], v[2:3] op_sel_hi:[1,0]
	v_pk_mul_f32 v[74:75], v[42:43], v[2:3] op_sel_hi:[1,0]
	v_mul_f32_e32 v71, 0xbfb8aa3b, v76
	v_exp_f32_e32 v71, v71
	s_nop 0
	v_add_f32_e32 v71, 1.0, v71
	v_rcp_f32_e32 v78, v71
	v_mul_f32_e32 v71, 0xbfb8aa3b, v77
	v_exp_f32_e32 v71, v71
	s_nop 0
	v_add_f32_e32 v71, 1.0, v71
	v_rcp_f32_e32 v79, v71
	v_mul_f32_e32 v71, 0xbfb8aa3b, v74
	v_exp_f32_e32 v71, v71
	v_pk_mul_f32 v[76:77], v[76:77], v[78:79]
	v_add_f32_e32 v71, 1.0, v71
	v_rcp_f32_e32 v78, v71
	v_mul_f32_e32 v71, 0xbfb8aa3b, v75
	v_exp_f32_e32 v71, v71
	s_nop 0
	v_add_f32_e32 v71, 1.0, v71
	v_rcp_f32_e32 v79, v71
	s_nop 0
	v_pk_mul_f32 v[74:75], v[74:75], v[78:79]
	v_pk_mul_f32 v[78:79], v[38:39], v[2:3] op_sel_hi:[1,0]
	v_mul_f32_e32 v2, 0xbfb8aa3b, v80
	v_exp_f32_e32 v2, v2
	s_nop 0
	v_add_f32_e32 v2, 1.0, v2
	v_rcp_f32_e32 v82, v2
	v_mul_f32_e32 v2, 0xbfb8aa3b, v81
	v_exp_f32_e32 v2, v2
	s_nop 0
	v_add_f32_e32 v2, 1.0, v2
	v_rcp_f32_e32 v83, v2
	v_mul_f32_e32 v2, 0xbfb8aa3b, v78
	v_exp_f32_e32 v2, v2
	v_pk_mul_f32 v[80:81], v[80:81], v[82:83]
	v_add_f32_e32 v2, 1.0, v2
	v_rcp_f32_e32 v82, v2
	v_mul_f32_e32 v2, 0xbfb8aa3b, v79
	v_exp_f32_e32 v2, v2
	s_nop 0
	v_add_f32_e32 v2, 1.0, v2
	v_rcp_f32_e32 v83, v2
	s_nop 0
	v_pk_mul_f32 v[78:79], v[78:79], v[82:83]
	v_lshl_add_u64 v[82:83], v[72:73], 0, v[68:69]
	v_cvt_pk_bf16_f32 v72, v76, v77
	v_add_co_u32_e32 v76, vcc, 0x643f000, v82
	v_cvt_pk_bf16_f32 v73, v74, v75
	v_cvt_pk_bf16_f32 v74, v80, v81
	v_cvt_pk_bf16_f32 v75, v78, v79
	v_addc_co_u32_e32 v77, vcc, 0, v83, vcc
	global_store_dwordx4 v[76:77], v[72:75], off offset:256
	s_cbranch_scc1 .LBB0_228
	v_add_u32_e32 v78, 0x80, v70
	v_ashrrev_i32_e32 v79, 31, v78
	v_lshl_add_u64 v[80:81], v[78:79], 2, s[70:71]
	v_mov_b32_e32 v84, v246
	v_mov_b32_e32 v82, v247
	v_mov_b32_e32 v74, v248
	v_mov_b32_e32 v2, v249
	v_lshlrev_b64 v[78:79], 11, v[78:79]
	v_lshl_add_u64 v[78:79], s[94:95], 0, v[78:79]
	v_add_u32_e32 v76, 0x90, v70
	v_ashrrev_i32_e32 v77, 31, v76
	v_lshlrev_b64 v[76:77], 11, v[76:77]
	v_lshl_add_u64 v[76:77], s[94:95], 0, v[76:77]
	v_add_u32_e32 v72, 0xa0, v70
	v_ashrrev_i32_e32 v73, 31, v72
	v_lshlrev_b64 v[72:73], 11, v[72:73]
	v_lshl_add_u64 v[72:73], s[94:95], 0, v[72:73]
	v_add_u32_e32 v70, 0xb0, v70
	v_ashrrev_i32_e32 v71, 31, v70
	v_lshlrev_b64 v[70:71], 11, v[70:71]
	v_lshl_add_u64 v[70:71], s[94:95], 0, v[70:71]
	v_pk_mul_f32 v[86:87], v[32:33], v[84:85] op_sel_hi:[1,0]
	s_nop 0
	v_mul_f32_e32 v75, 0xbfb8aa3b, v86
	v_exp_f32_e32 v75, v75
	v_pk_mul_f32 v[80:81], v[34:35], v[84:85] op_sel_hi:[1,0]
	v_add_f32_e32 v75, 1.0, v75
	v_rcp_f32_e32 v88, v75
	v_mul_f32_e32 v75, 0xbfb8aa3b, v87
	v_exp_f32_e32 v75, v75
	s_nop 0
	v_add_f32_e32 v75, 1.0, v75
	v_rcp_f32_e32 v89, v75
	v_mul_f32_e32 v75, 0xbfb8aa3b, v80
	v_exp_f32_e32 v75, v75
	v_pk_mul_f32 v[86:87], v[86:87], v[88:89]
	v_add_f32_e32 v75, 1.0, v75
	v_rcp_f32_e32 v88, v75
	v_mul_f32_e32 v75, 0xbfb8aa3b, v81
	v_exp_f32_e32 v75, v75
	s_nop 0
	v_add_f32_e32 v75, 1.0, v75
	v_rcp_f32_e32 v89, v75
	s_nop 0
	v_pk_mul_f32 v[80:81], v[80:81], v[88:89]
	v_pk_mul_f32 v[88:89], v[30:31], v[84:85] op_sel_hi:[1,0]
	v_pk_mul_f32 v[84:85], v[28:29], v[84:85] op_sel_hi:[1,0]
	s_nop 0
	v_mul_f32_e32 v75, 0xbfb8aa3b, v84
	v_exp_f32_e32 v75, v75
	s_nop 0
	v_add_f32_e32 v75, 1.0, v75
	v_rcp_f32_e32 v90, v75
	v_mul_f32_e32 v75, 0xbfb8aa3b, v85
	v_exp_f32_e32 v75, v75
	s_nop 0
	v_add_f32_e32 v75, 1.0, v75
	v_rcp_f32_e32 v91, v75
	v_mul_f32_e32 v75, 0xbfb8aa3b, v88
	v_exp_f32_e32 v75, v75
	v_pk_mul_f32 v[84:85], v[84:85], v[90:91]
	v_add_f32_e32 v75, 1.0, v75
	v_rcp_f32_e32 v90, v75
	v_mul_f32_e32 v75, 0xbfb8aa3b, v89
	v_exp_f32_e32 v75, v75
	s_nop 0
	v_add_f32_e32 v75, 1.0, v75
	v_rcp_f32_e32 v91, v75
	s_nop 0
	v_pk_mul_f32 v[88:89], v[88:89], v[90:91]
	v_lshl_add_u64 v[90:91], v[78:79], 0, v[68:69]
	v_cvt_pk_bf16_f32 v79, v80, v81
	v_cvt_pk_bf16_f32 v80, v84, v85
	v_add_co_u32_e32 v84, vcc, s0, v90
	v_cvt_pk_bf16_f32 v78, v86, v87
	v_cvt_pk_bf16_f32 v81, v88, v89
	v_addc_co_u32_e32 v85, vcc, 0, v91, vcc
	global_store_dwordx4 v[84:85], v[78:81], off offset:256
	s_nop 1
	v_pk_mul_f32 v[78:79], v[24:25], v[82:83] op_sel_hi:[1,0]
	v_pk_mul_f32 v[80:81], v[26:27], v[82:83] op_sel_hi:[1,0]
	v_mul_f32_e32 v75, 0xbfb8aa3b, v78
	v_exp_f32_e32 v75, v75
	s_nop 0
	v_add_f32_e32 v75, 1.0, v75
	v_rcp_f32_e32 v84, v75
	v_mul_f32_e32 v75, 0xbfb8aa3b, v79
	v_exp_f32_e32 v75, v75
	s_nop 0
	v_add_f32_e32 v75, 1.0, v75
	v_rcp_f32_e32 v85, v75
	v_mul_f32_e32 v75, 0xbfb8aa3b, v80
	v_exp_f32_e32 v75, v75
	v_pk_mul_f32 v[78:79], v[78:79], v[84:85]
	v_add_f32_e32 v75, 1.0, v75
	v_rcp_f32_e32 v84, v75
	v_mul_f32_e32 v75, 0xbfb8aa3b, v81
	v_exp_f32_e32 v75, v75
	s_nop 0
	v_add_f32_e32 v75, 1.0, v75
	v_rcp_f32_e32 v85, v75
	s_nop 0
	v_pk_mul_f32 v[80:81], v[80:81], v[84:85]
	v_pk_mul_f32 v[84:85], v[22:23], v[82:83] op_sel_hi:[1,0]
	v_pk_mul_f32 v[82:83], v[20:21], v[82:83] op_sel_hi:[1,0]
	s_nop 0
	v_mul_f32_e32 v75, 0xbfb8aa3b, v82
	v_exp_f32_e32 v75, v75
	s_nop 0
	v_add_f32_e32 v75, 1.0, v75
	v_rcp_f32_e32 v86, v75
	v_mul_f32_e32 v75, 0xbfb8aa3b, v83
	v_exp_f32_e32 v75, v75
	s_nop 0
	v_add_f32_e32 v75, 1.0, v75
	v_rcp_f32_e32 v87, v75
	v_mul_f32_e32 v75, 0xbfb8aa3b, v84
	v_exp_f32_e32 v75, v75
	v_pk_mul_f32 v[82:83], v[82:83], v[86:87]
	v_add_f32_e32 v75, 1.0, v75
	v_rcp_f32_e32 v86, v75
	v_mul_f32_e32 v75, 0xbfb8aa3b, v85
	v_exp_f32_e32 v75, v75
	s_nop 0
	v_add_f32_e32 v75, 1.0, v75
	v_rcp_f32_e32 v87, v75
	s_nop 0
	v_pk_mul_f32 v[84:85], v[84:85], v[86:87]
	v_lshl_add_u64 v[86:87], v[76:77], 0, v[68:69]
	v_cvt_pk_bf16_f32 v77, v80, v81
	v_add_co_u32_e32 v80, vcc, s0, v86
	v_cvt_pk_bf16_f32 v76, v78, v79
	v_cvt_pk_bf16_f32 v78, v82, v83
	v_cvt_pk_bf16_f32 v79, v84, v85
	v_addc_co_u32_e32 v81, vcc, 0, v87, vcc
	global_store_dwordx4 v[80:81], v[76:79], off offset:256
	s_nop 1
	v_pk_mul_f32 v[78:79], v[16:17], v[74:75] op_sel_hi:[1,0]
	v_pk_mul_f32 v[76:77], v[18:19], v[74:75] op_sel_hi:[1,0]
	v_mul_f32_e32 v75, 0xbfb8aa3b, v78
	v_exp_f32_e32 v75, v75
	s_nop 0
	v_add_f32_e32 v75, 1.0, v75
	v_rcp_f32_e32 v80, v75
	v_mul_f32_e32 v75, 0xbfb8aa3b, v79
	v_exp_f32_e32 v75, v75
	s_nop 0
	v_add_f32_e32 v75, 1.0, v75
	v_rcp_f32_e32 v81, v75
	v_mul_f32_e32 v75, 0xbfb8aa3b, v76
	v_exp_f32_e32 v75, v75
	v_pk_mul_f32 v[78:79], v[78:79], v[80:81]
	v_add_f32_e32 v75, 1.0, v75
	v_rcp_f32_e32 v80, v75
	v_mul_f32_e32 v75, 0xbfb8aa3b, v77
	v_exp_f32_e32 v75, v75
	s_nop 0
	v_add_f32_e32 v75, 1.0, v75
	v_rcp_f32_e32 v81, v75
	s_nop 0
	v_pk_mul_f32 v[76:77], v[76:77], v[80:81]
	v_pk_mul_f32 v[80:81], v[14:15], v[74:75] op_sel_hi:[1,0]
	v_pk_mul_f32 v[74:75], v[12:13], v[74:75] op_sel_hi:[1,0]
	s_nop 0
	v_mul_f32_e32 v82, 0xbfb8aa3b, v74
	v_mul_f32_e32 v83, 0xbfb8aa3b, v75
	v_exp_f32_e32 v82, v82
	v_exp_f32_e32 v83, v83
	v_add_f32_e32 v82, 1.0, v82
	v_add_f32_e32 v83, 1.0, v83
	v_rcp_f32_e32 v82, v82
	v_rcp_f32_e32 v83, v83
	s_nop 0
	v_pk_mul_f32 v[74:75], v[74:75], v[82:83]
	v_mul_f32_e32 v82, 0xbfb8aa3b, v80
	v_mul_f32_e32 v83, 0xbfb8aa3b, v81
	v_exp_f32_e32 v82, v82
	v_exp_f32_e32 v83, v83
	v_cvt_pk_bf16_f32 v74, v74, v75
	v_add_f32_e32 v82, 1.0, v82
	v_add_f32_e32 v83, 1.0, v83
	v_rcp_f32_e32 v82, v82
	v_rcp_f32_e32 v83, v83
	s_nop 0
	v_pk_mul_f32 v[80:81], v[80:81], v[82:83]
	v_lshl_add_u64 v[82:83], v[72:73], 0, v[68:69]
	v_cvt_pk_bf16_f32 v73, v76, v77
	v_add_co_u32_e32 v76, vcc, s0, v82
	v_cvt_pk_bf16_f32 v72, v78, v79
	v_cvt_pk_bf16_f32 v75, v80, v81
	v_addc_co_u32_e32 v77, vcc, 0, v83, vcc
	global_store_dwordx4 v[76:77], v[72:75], off offset:256
	v_pk_mul_f32 v[78:79], v[4:5], v[2:3] op_sel_hi:[1,0]
	s_mov_b64 s[0:1], 0
	v_pk_mul_f32 v[74:75], v[8:9], v[2:3] op_sel_hi:[1,0]
	v_pk_mul_f32 v[72:73], v[10:11], v[2:3] op_sel_hi:[1,0]
	v_mul_f32_e32 v76, 0xbfb8aa3b, v74
	v_mul_f32_e32 v77, 0xbfb8aa3b, v75
	v_exp_f32_e32 v76, v76
	v_exp_f32_e32 v77, v77
	v_add_f32_e32 v76, 1.0, v76
	v_add_f32_e32 v77, 1.0, v77
	v_rcp_f32_e32 v76, v76
	v_rcp_f32_e32 v77, v77
	s_nop 0
	v_pk_mul_f32 v[74:75], v[74:75], v[76:77]
	v_mul_f32_e32 v76, 0xbfb8aa3b, v72
	v_mul_f32_e32 v77, 0xbfb8aa3b, v73
	v_exp_f32_e32 v76, v76
	v_exp_f32_e32 v77, v77
	v_add_f32_e32 v76, 1.0, v76
	v_add_f32_e32 v77, 1.0, v77
	v_rcp_f32_e32 v76, v76
	v_rcp_f32_e32 v77, v77
	s_nop 0
	v_pk_mul_f32 v[72:73], v[72:73], v[76:77]
	v_pk_mul_f32 v[76:77], v[6:7], v[2:3] op_sel_hi:[1,0]
	v_mul_f32_e32 v2, 0xbfb8aa3b, v78
	v_exp_f32_e32 v2, v2
	s_nop 0
	v_add_f32_e32 v2, 1.0, v2
	v_rcp_f32_e32 v80, v2
	v_mul_f32_e32 v2, 0xbfb8aa3b, v79
	v_exp_f32_e32 v2, v2
	s_nop 0
	v_add_f32_e32 v2, 1.0, v2
	v_rcp_f32_e32 v81, v2
	v_mul_f32_e32 v2, 0xbfb8aa3b, v76
	v_exp_f32_e32 v2, v2
	v_pk_mul_f32 v[78:79], v[78:79], v[80:81]
	v_add_f32_e32 v2, 1.0, v2
	v_rcp_f32_e32 v80, v2
	v_mul_f32_e32 v2, 0xbfb8aa3b, v77
	v_exp_f32_e32 v2, v2
	s_nop 0
	v_add_f32_e32 v2, 1.0, v2
	v_rcp_f32_e32 v81, v2
	s_nop 0
	v_pk_mul_f32 v[76:77], v[76:77], v[80:81]
	v_lshl_add_u64 v[80:81], v[70:71], 0, v[68:69]
	v_cvt_pk_bf16_f32 v69, v72, v73
	v_add_co_u32_e32 v72, vcc, 0x643f000, v80
	v_cvt_pk_bf16_f32 v68, v74, v75
	v_cvt_pk_bf16_f32 v70, v78, v79
	v_cvt_pk_bf16_f32 v71, v76, v77
	v_addc_co_u32_e32 v73, vcc, 0, v81, vcc
	global_store_dwordx4 v[72:73], v[68:71], off offset:256
	s_branch .LBB0_229
